# v11 (C=0 first K-iteration instead of acc zeroing) + compact packed rglru conv segment
# baseline (speedup 1.0000x reference)
; #define PG8_STAGE(bufoff, gbase, voff) do { _Pragma("unroll") for (int _i = 0; _i < 2; ++_i) \
;         __builtin_amdgcn_global_load_lds((const unsigned*)((const char*)(gbase) + (voff)[_i]), (PG8_LAS unsigned*)(lds + (bufoff) + ldsw + _i * 8192), 16, 0, 0); } while (0)
; #define PG8_LDA(dst, b, h) do { _Pragma("unroll") for (int m = 0; m < 4; ++m) _Pragma("unroll") for (int k = 0; k < 2; ++k) dst[m][k] = *(const PG8_LAS bf16x8*)(lds + PG8_SA(b, h) + aoff + m * 2048 + k * 1024); } while (0)
; #define PG8_LDB(dst, b, h) do { _Pragma("unroll") for (int n = 0; n < 2; ++n) _Pragma("unroll") for (int k = 0; k < 2; ++k) dst[n][k] = *(const PG8_LAS bf16x8*)(lds + PG8_SB(b, h) + boff + n * 2048 + k * 1024); } while (0)
; #define PG8_MMA(ai, bj, At, Bt) do { __builtin_amdgcn_s_setprio(1); _Pragma("unroll") for (int m = 0; m < 4; ++m) _Pragma("unroll") for (int n = 0; n < 2; ++n) _Pragma("unroll") for (int k = 0; k < 2; ++k) \
;         acc[ai][bj][m][n] = __builtin_amdgcn_mfma_f32_16x16x32_bf16(Bt[n][k], At[m][k], acc[ai][bj][m][n], 0, 0, 0); __builtin_amdgcn_s_setprio(0); } while (0)
; #define PG8_WAIT_V(n) asm volatile("s_waitcnt vmcnt(" #n ")" ::: "memory")
; #define PG8_WAIT_L(n) asm volatile("s_waitcnt lgkmcnt(" #n ")" ::: "memory")
; #define PG8_BAR __builtin_amdgcn_s_barrier()
; #define PG8_SCHED __builtin_amdgcn_sched_barrier(0)
; template <class Epi, class Sched, bool ALIGN_EPI = false, bool SP2 = false>
; __device__ __forceinline__ void gemm_phase(PG8_LAS unsigned char* lds, const Gemm g, const Sched& S, const Epi& E) {
;     ...
;             const char* a1 = cA + (size_t)(t + 1) * kstep;
;             const char* a2 = last ? nA : cA + (size_t)(t + 2) * kstep; const char* b2 = last ? nB : cB + (size_t)(t + 2) * kstep;
;             const char* a3 = a2 + kstep; const char* b3 = b2 + kstep;
;             if (last && has_next) S.a_ready_inloop(nxt, ui + 1);
;             if constexpr (SP2) {
;             PG8_LDB(B0, 0, 0); PG8_LDB(B1, 0, 1); PG8_SCHED; PG8_LDA(At, 0, 0); PG8_STAGE(PG8_SA(1, 1), a1 + hstep, voffA);
;             PG8_WAIT_V(8); PG8_WAIT_L(0); PG8_BAR; PG8_MMA(0, 0, At, B0); PG8_MMA(0, 1, At, B1); PG8_BAR; PG8_SCHED;
;             PG8_LDA(At, 0, 1); PG8_STAGE(PG8_SB(0, 0), b2, voffB); PG8_STAGE(PG8_SB(0, 1), b2 + hstep, voffB); PG8_STAGE(PG8_SA(0, 0), a2, voffA);
.LBB0_120:
	s_ashr_i32 s13, s12, 31
	s_lshl_b64 s[16:17], s[12:13], 19
	s_add_u32 s16, s28, s16
	s_addc_u32 s17, s29, s17
	s_and_b64 s[18:19], s[2:3], exec
	s_cselect_b32 s13, s17, s21
	s_cselect_b32 s52, s16, s20
	s_ashr_i32 s15, s14, 31
	s_lshl_b64 s[18:19], s[14:15], 19
	s_add_u32 s18, s30, s18
	s_addc_u32 s19, s31, s19
	s_and_b64 s[24:25], s[2:3], exec
	s_cselect_b32 s15, s19, s23
	s_cselect_b32 s53, s18, s22
	s_add_u32 s20, s20, 0x40080
	s_addc_u32 s21, s21, 0
	s_add_u32 s62, s22, 0x100
	s_addc_u32 s63, s23, 0
	s_mov_b32 s64, -2
	s_add_u32 s22, s20, 0xfffc0080
	s_addc_u32 s23, s21, -1
	s_add_i32 s90, 0, 0x10000
	s_cmp_eq_u32 s64, 12
	s_cselect_b32 s25, s13, s23
	s_cselect_b32 s24, s52, s22
	v_add_u32_e32 v158, s90, v160
	s_cselect_b32 s23, s15, s63
	s_cselect_b32 s22, s53, s62
	s_add_i32 s81, 0, 0x14000
	ds_read_b128 v[164:167], v158
	ds_read_b128 v[168:171], v158 offset:1024
	ds_read_b128 v[172:175], v158 offset:2048
	ds_read_b128 v[176:179], v158 offset:3072
	v_add_u32_e32 v158, s81, v160
	ds_read_b128 v[180:183], v158
	ds_read_b128 v[184:187], v158 offset:1024
	ds_read_b128 v[188:191], v158 offset:2048
	ds_read_b128 v[192:195], v158 offset:3072
	v_lshl_add_u64 v[158:159], s[20:21], 0, v[154:155]
	s_add_i32 m0, s35, 0xc000
	ds_read_b128 v[196:199], v163
	ds_read_b128 v[200:203], v163 offset:1024
	ds_read_b128 v[216:219], v163 offset:2048
	ds_read_b128 v[220:223], v163 offset:3072
	ds_read_b128 v[224:227], v163 offset:4096
	ds_read_b128 v[228:231], v163 offset:5120
	ds_read_b128 v[232:235], v163 offset:6144
	ds_read_b128 v[236:239], v163 offset:7168
	global_load_lds_dwordx4 v[158:159], off
	v_lshl_add_u64 v[158:159], s[20:21], 0, v[156:157]
	s_add_i32 m0, s35, 0xe000
	s_nop 0
	global_load_lds_dwordx4 v[158:159], off
	s_waitcnt vmcnt(8)
	s_waitcnt lgkmcnt(0)
	s_barrier
	s_setprio 1
	s_waitcnt lgkmcnt(0)
	v_mfma_f32_16x16x32_bf16 v[142:145], v[164:167], v[196:199], 0
	v_mfma_f32_16x16x32_bf16 v[138:141], v[172:175], v[196:199], 0
	v_mfma_f32_16x16x32_bf16 v[126:129], v[164:167], v[216:219], 0
	v_mfma_f32_16x16x32_bf16 v[122:125], v[172:175], v[216:219], 0
	v_mfma_f32_16x16x32_bf16 v[110:113], v[164:167], v[224:227], 0
	v_mfma_f32_16x16x32_bf16 v[106:109], v[172:175], v[224:227], 0
	v_mfma_f32_16x16x32_bf16 v[94:97], v[164:167], v[232:235], 0
	v_mfma_f32_16x16x32_bf16 v[90:93], v[172:175], v[232:235], 0
	v_mfma_f32_16x16x32_bf16 v[142:145], v[168:171], v[200:203], v[142:145]
	v_mfma_f32_16x16x32_bf16 v[138:141], v[176:179], v[200:203], v[138:141]
	v_mfma_f32_16x16x32_bf16 v[126:129], v[168:171], v[220:223], v[126:129]
	v_mfma_f32_16x16x32_bf16 v[122:125], v[176:179], v[220:223], v[122:125]
	v_mfma_f32_16x16x32_bf16 v[110:113], v[168:171], v[228:231], v[110:113]
	v_mfma_f32_16x16x32_bf16 v[106:109], v[176:179], v[228:231], v[106:109]
	v_mfma_f32_16x16x32_bf16 v[94:97], v[168:171], v[236:239], v[94:97]
	v_mfma_f32_16x16x32_bf16 v[90:93], v[176:179], v[236:239], v[90:93]
	s_setprio 0
	s_setprio 1
	v_mfma_f32_16x16x32_bf16 v[134:137], v[180:183], v[196:199], 0
	v_mfma_f32_16x16x32_bf16 v[130:133], v[188:191], v[196:199], 0
	v_mfma_f32_16x16x32_bf16 v[118:121], v[180:183], v[216:219], 0
	v_mfma_f32_16x16x32_bf16 v[114:117], v[188:191], v[216:219], 0
	v_mfma_f32_16x16x32_bf16 v[102:105], v[180:183], v[224:227], 0
	v_mfma_f32_16x16x32_bf16 v[98:101], v[188:191], v[224:227], 0
	v_mfma_f32_16x16x32_bf16 v[86:89], v[180:183], v[232:235], 0
	v_mfma_f32_16x16x32_bf16 v[82:85], v[188:191], v[232:235], 0
	v_mfma_f32_16x16x32_bf16 v[134:137], v[184:187], v[200:203], v[134:137]
	v_mfma_f32_16x16x32_bf16 v[130:133], v[192:195], v[200:203], v[130:133]
	v_mfma_f32_16x16x32_bf16 v[118:121], v[184:187], v[220:223], v[118:121]
	v_mfma_f32_16x16x32_bf16 v[114:117], v[192:195], v[220:223], v[114:117]
	v_mfma_f32_16x16x32_bf16 v[102:105], v[184:187], v[228:231], v[102:105]
	v_mfma_f32_16x16x32_bf16 v[98:101], v[192:195], v[228:231], v[98:101]
	v_mfma_f32_16x16x32_bf16 v[86:89], v[184:187], v[236:239], v[86:89]
	v_mfma_f32_16x16x32_bf16 v[82:85], v[192:195], v[236:239], v[82:85]
	s_setprio 0
	s_barrier
	s_add_i32 s65, s90, s34
	v_lshl_add_u64 v[158:159], s[22:23], 0, v[148:149]
	s_mov_b32 m0, s65
	ds_read_b128 v[196:199], v163 offset:16384
	ds_read_b128 v[200:203], v163 offset:17408
	ds_read_b128 v[216:219], v163 offset:18432
	ds_read_b128 v[220:223], v163 offset:19456
	ds_read_b128 v[224:227], v163 offset:20480
	ds_read_b128 v[228:231], v163 offset:21504
	ds_read_b128 v[232:235], v163 offset:22528
	ds_read_b128 v[236:239], v163 offset:23552
	global_load_lds_dwordx4 v[158:159], off
	s_add_i32 m0, s65, 0x2000
	s_add_u32 s66, s22, 0x40000
	v_lshl_add_u64 v[240:241], s[22:23], 0, v[152:153]
	s_addc_u32 s67, s23, 0
	s_add_i32 s65, s81, s34
	global_load_lds_dwordx4 v[240:241], off
	v_lshl_add_u64 v[242:243], s[66:67], 0, v[148:149]
	s_mov_b32 m0, s65
	v_lshl_add_u64 v[244:245], s[24:25], 0, v[150:151]
	global_load_lds_dwordx4 v[242:243], off
	v_lshl_add_u64 v[242:243], s[66:67], 0, v[152:153]
	s_add_i32 m0, s65, 0x2000
	s_nop 0
	global_load_lds_dwordx4 v[242:243], off
	v_lshl_add_u64 v[242:243], s[24:25], 0, v[146:147]
	s_mov_b32 m0, s35
	s_nop 0
	global_load_lds_dwordx4 v[242:243], off
	s_mov_b32 m0, s36
	s_nop 0
	global_load_lds_dwordx4 v[244:245], off
	s_waitcnt vmcnt(8)
	s_waitcnt lgkmcnt(0)
	s_barrier
; #define PG8_STAGE(bufoff, gbase, voff) do { _Pragma("unroll") for (int _i = 0; _i < 2; ++_i) \
;         __builtin_amdgcn_global_load_lds((const unsigned*)((const char*)(gbase) + (voff)[_i]), (PG8_LAS unsigned*)(lds + (bufoff) + ldsw + _i * 8192), 16, 0, 0); } while (0)
; #define PG8_LDA(dst, b, h) do { _Pragma("unroll") for (int m = 0; m < 4; ++m) _Pragma("unroll") for (int k = 0; k < 2; ++k) dst[m][k] = *(const PG8_LAS bf16x8*)(lds + PG8_SA(b, h) + aoff + m * 2048 + k * 1024); } while (0)
; #define PG8_LDB(dst, b, h) do { _Pragma("unroll") for (int n = 0; n < 2; ++n) _Pragma("unroll") for (int k = 0; k < 2; ++k) dst[n][k] = *(const PG8_LAS bf16x8*)(lds + PG8_SB(b, h) + boff + n * 2048 + k * 1024); } while (0)
; #define PG8_MMA(ai, bj, At, Bt) do { __builtin_amdgcn_s_setprio(1); _Pragma("unroll") for (int m = 0; m < 4; ++m) _Pragma("unroll") for (int n = 0; n < 2; ++n) _Pragma("unroll") for (int k = 0; k < 2; ++k) \
;         acc[ai][bj][m][n] = __builtin_amdgcn_mfma_f32_16x16x32_bf16(Bt[n][k], At[m][k], acc[ai][bj][m][n], 0, 0, 0); __builtin_amdgcn_s_setprio(0); } while (0)
; #define PG8_WAIT_V(n) asm volatile("s_waitcnt vmcnt(" #n ")" ::: "memory")
; #define PG8_WAIT_L(n) asm volatile("s_waitcnt lgkmcnt(" #n ")" ::: "memory")
; #define PG8_BAR __builtin_amdgcn_s_barrier()
; #define PG8_SCHED __builtin_amdgcn_sched_barrier(0)
; template <class Epi, class Sched, bool ALIGN_EPI = false, bool SP2 = false>
; __device__ __forceinline__ void gemm_phase(PG8_LAS unsigned char* lds, const Gemm g, const Sched& S, const Epi& E) {
;     ...
;             PG8_WAIT_V(8); PG8_WAIT_L(0); PG8_BAR; PG8_MMA(1, 0, At, B0); PG8_MMA(1, 1, At, B1); PG8_BAR; PG8_SCHED;
;             PG8_LDB(B0, 1, 0); PG8_LDB(B1, 1, 1); PG8_SCHED; PG8_LDA(At, 1, 0); PG8_STAGE(PG8_SA(0, 1), a2 + hstep, voffA);
;             PG8_WAIT_V(8); PG8_WAIT_L(0); PG8_BAR; PG8_MMA(0, 0, At, B0); PG8_MMA(0, 1, At, B1); PG8_BAR; PG8_SCHED;
	s_setprio 1
	s_waitcnt lgkmcnt(0)
	v_mfma_f32_16x16x32_bf16 v[78:81], v[164:167], v[196:199], 0
	v_mfma_f32_16x16x32_bf16 v[74:77], v[172:175], v[196:199], 0
	v_mfma_f32_16x16x32_bf16 v[62:65], v[164:167], v[216:219], 0
	v_mfma_f32_16x16x32_bf16 v[58:61], v[172:175], v[216:219], 0
	v_mfma_f32_16x16x32_bf16 v[46:49], v[164:167], v[224:227], 0
	v_mfma_f32_16x16x32_bf16 v[42:45], v[172:175], v[224:227], 0
	v_mfma_f32_16x16x32_bf16 v[30:33], v[164:167], v[232:235], 0
	v_mfma_f32_16x16x32_bf16 v[26:29], v[172:175], v[232:235], 0
	v_mfma_f32_16x16x32_bf16 v[78:81], v[168:171], v[200:203], v[78:81]
	v_mfma_f32_16x16x32_bf16 v[74:77], v[176:179], v[200:203], v[74:77]
	v_mfma_f32_16x16x32_bf16 v[62:65], v[168:171], v[220:223], v[62:65]
	v_mfma_f32_16x16x32_bf16 v[58:61], v[176:179], v[220:223], v[58:61]
	v_mfma_f32_16x16x32_bf16 v[46:49], v[168:171], v[228:231], v[46:49]
	v_mfma_f32_16x16x32_bf16 v[42:45], v[176:179], v[228:231], v[42:45]
	v_mfma_f32_16x16x32_bf16 v[30:33], v[168:171], v[236:239], v[30:33]
	v_mfma_f32_16x16x32_bf16 v[26:29], v[176:179], v[236:239], v[26:29]
	s_setprio 0
	s_setprio 1
	v_mfma_f32_16x16x32_bf16 v[70:73], v[180:183], v[196:199], 0
	v_mfma_f32_16x16x32_bf16 v[66:69], v[188:191], v[196:199], 0
	v_mfma_f32_16x16x32_bf16 v[54:57], v[180:183], v[216:219], 0
	v_mfma_f32_16x16x32_bf16 v[50:53], v[188:191], v[216:219], 0
	v_mfma_f32_16x16x32_bf16 v[38:41], v[180:183], v[224:227], 0
	v_mfma_f32_16x16x32_bf16 v[34:37], v[188:191], v[224:227], 0
	v_mfma_f32_16x16x32_bf16 v[22:25], v[180:183], v[232:235], 0
	v_mfma_f32_16x16x32_bf16 v[18:21], v[188:191], v[232:235], 0
	v_mfma_f32_16x16x32_bf16 v[70:73], v[184:187], v[200:203], v[70:73]
	v_mfma_f32_16x16x32_bf16 v[66:69], v[192:195], v[200:203], v[66:69]
	v_mfma_f32_16x16x32_bf16 v[54:57], v[184:187], v[220:223], v[54:57]
	v_mfma_f32_16x16x32_bf16 v[50:53], v[192:195], v[220:223], v[50:53]
	v_mfma_f32_16x16x32_bf16 v[38:41], v[184:187], v[228:231], v[38:41]
	v_mfma_f32_16x16x32_bf16 v[34:37], v[192:195], v[228:231], v[34:37]
	v_mfma_f32_16x16x32_bf16 v[22:25], v[184:187], v[236:239], v[22:25]
	v_mfma_f32_16x16x32_bf16 v[18:21], v[192:195], v[236:239], v[18:21]
	s_setprio 0
	s_barrier
	s_add_i32 s82, 0, 0x18000
	s_add_i32 s83, 0, 0x1c000
	v_add_u32_e32 v176, s82, v160
	v_add_u32_e32 v192, s83, v160
	ds_read_b128 v[164:167], v176
	ds_read_b128 v[168:171], v176 offset:1024
	ds_read_b128 v[172:175], v176 offset:2048
	ds_read_b128 v[176:179], v176 offset:3072
	ds_read_b128 v[180:183], v192
	ds_read_b128 v[184:187], v192 offset:1024
	ds_read_b128 v[188:191], v192 offset:2048
	ds_read_b128 v[192:195], v192 offset:3072
	s_add_u32 s24, s24, 0x40000
	s_addc_u32 s25, s25, 0
	s_mov_b32 m0, s37
	v_lshl_add_u64 v[246:247], s[24:25], 0, v[146:147]
	ds_read_b128 v[196:199], v163 offset:32768
	ds_read_b128 v[200:203], v163 offset:33792
	ds_read_b128 v[216:219], v163 offset:34816
	ds_read_b128 v[220:223], v163 offset:35840
	ds_read_b128 v[224:227], v163 offset:36864
	ds_read_b128 v[228:231], v163 offset:37888
	ds_read_b128 v[232:235], v163 offset:38912
	ds_read_b128 v[236:239], v163 offset:39936
	global_load_lds_dwordx4 v[246:247], off
	v_lshl_add_u64 v[246:247], s[24:25], 0, v[150:151]
	s_mov_b32 m0, s38
	s_nop 0
	global_load_lds_dwordx4 v[246:247], off
	s_waitcnt vmcnt(8)
	s_waitcnt lgkmcnt(0)
	s_barrier
	s_setprio 1
	s_waitcnt lgkmcnt(0)
	v_mfma_f32_16x16x32_bf16 v[142:145], v[164:167], v[196:199], v[142:145]
	v_mfma_f32_16x16x32_bf16 v[138:141], v[172:175], v[196:199], v[138:141]
	v_mfma_f32_16x16x32_bf16 v[126:129], v[164:167], v[216:219], v[126:129]
	v_mfma_f32_16x16x32_bf16 v[122:125], v[172:175], v[216:219], v[122:125]
	v_mfma_f32_16x16x32_bf16 v[110:113], v[164:167], v[224:227], v[110:113]
	v_mfma_f32_16x16x32_bf16 v[106:109], v[172:175], v[224:227], v[106:109]
	v_mfma_f32_16x16x32_bf16 v[94:97], v[164:167], v[232:235], v[94:97]
	v_mfma_f32_16x16x32_bf16 v[90:93], v[172:175], v[232:235], v[90:93]
	v_mfma_f32_16x16x32_bf16 v[142:145], v[168:171], v[200:203], v[142:145]
	v_mfma_f32_16x16x32_bf16 v[138:141], v[176:179], v[200:203], v[138:141]
	v_mfma_f32_16x16x32_bf16 v[126:129], v[168:171], v[220:223], v[126:129]
	v_mfma_f32_16x16x32_bf16 v[122:125], v[176:179], v[220:223], v[122:125]
	v_mfma_f32_16x16x32_bf16 v[110:113], v[168:171], v[228:231], v[110:113]
	v_mfma_f32_16x16x32_bf16 v[106:109], v[176:179], v[228:231], v[106:109]
	v_mfma_f32_16x16x32_bf16 v[94:97], v[168:171], v[236:239], v[94:97]
	v_mfma_f32_16x16x32_bf16 v[90:93], v[176:179], v[236:239], v[90:93]
	s_setprio 0
	s_setprio 1
	v_mfma_f32_16x16x32_bf16 v[134:137], v[180:183], v[196:199], v[134:137]
	v_mfma_f32_16x16x32_bf16 v[130:133], v[188:191], v[196:199], v[130:133]
	v_mfma_f32_16x16x32_bf16 v[118:121], v[180:183], v[216:219], v[118:121]
	v_mfma_f32_16x16x32_bf16 v[114:117], v[188:191], v[216:219], v[114:117]
	v_mfma_f32_16x16x32_bf16 v[102:105], v[180:183], v[224:227], v[102:105]
	v_mfma_f32_16x16x32_bf16 v[98:101], v[188:191], v[224:227], v[98:101]
	v_mfma_f32_16x16x32_bf16 v[86:89], v[180:183], v[232:235], v[86:89]
	v_mfma_f32_16x16x32_bf16 v[82:85], v[188:191], v[232:235], v[82:85]
	v_mfma_f32_16x16x32_bf16 v[134:137], v[184:187], v[200:203], v[134:137]
	v_mfma_f32_16x16x32_bf16 v[130:133], v[192:195], v[200:203], v[130:133]
	v_mfma_f32_16x16x32_bf16 v[118:121], v[184:187], v[220:223], v[118:121]
	v_mfma_f32_16x16x32_bf16 v[114:117], v[192:195], v[220:223], v[114:117]
	v_mfma_f32_16x16x32_bf16 v[102:105], v[184:187], v[228:231], v[102:105]
	v_mfma_f32_16x16x32_bf16 v[98:101], v[192:195], v[228:231], v[98:101]
	v_mfma_f32_16x16x32_bf16 v[86:89], v[184:187], v[236:239], v[86:89]
	v_mfma_f32_16x16x32_bf16 v[82:85], v[192:195], v[236:239], v[82:85]
	s_setprio 0
	s_barrier
; #define PG8_STAGE(bufoff, gbase, voff) do { _Pragma("unroll") for (int _i = 0; _i < 2; ++_i) \
;         __builtin_amdgcn_global_load_lds((const unsigned*)((const char*)(gbase) + (voff)[_i]), (PG8_LAS unsigned*)(lds + (bufoff) + ldsw + _i * 8192), 16, 0, 0); } while (0)
; #define PG8_LDA(dst, b, h) do { _Pragma("unroll") for (int m = 0; m < 4; ++m) _Pragma("unroll") for (int k = 0; k < 2; ++k) dst[m][k] = *(const PG8_LAS bf16x8*)(lds + PG8_SA(b, h) + aoff + m * 2048 + k * 1024); } while (0)
; #define PG8_MMA(ai, bj, At, Bt) do { __builtin_amdgcn_s_setprio(1); _Pragma("unroll") for (int m = 0; m < 4; ++m) _Pragma("unroll") for (int n = 0; n < 2; ++n) _Pragma("unroll") for (int k = 0; k < 2; ++k) \
;         acc[ai][bj][m][n] = __builtin_amdgcn_mfma_f32_16x16x32_bf16(Bt[n][k], At[m][k], acc[ai][bj][m][n], 0, 0, 0); __builtin_amdgcn_s_setprio(0); } while (0)
; #define PG8_WAIT_V(n) asm volatile("s_waitcnt vmcnt(" #n ")" ::: "memory")
; #define PG8_WAIT_L(n) asm volatile("s_waitcnt lgkmcnt(" #n ")" ::: "memory")
; #define PG8_BAR __builtin_amdgcn_s_barrier()
; #define PG8_SCHED __builtin_amdgcn_sched_barrier(0)
; template <class Epi, class Sched, bool ALIGN_EPI = false, bool SP2 = false>
; __device__ __forceinline__ void gemm_phase(PG8_LAS unsigned char* lds, const Gemm g, const Sched& S, const Epi& E) {
;     ...
;             PG8_WAIT_V(8); PG8_WAIT_L(0); PG8_BAR; PG8_MMA(0, 0, At, B0); PG8_MMA(0, 1, At, B1); PG8_BAR; PG8_SCHED;
;             PG8_LDA(At, 1, 1); PG8_STAGE(PG8_SB(1, 0), b3, voffB); PG8_STAGE(PG8_SB(1, 1), b3 + hstep, voffB); PG8_STAGE(PG8_SA(1, 0), a3, voffA);
;             PG8_WAIT_V(8); PG8_WAIT_L(0); PG8_BAR; PG8_MMA(1, 0, At, B0); PG8_MMA(1, 1, At, B1); PG8_BAR; PG8_SCHED;
	s_add_i32 s24, s82, s34
	v_lshl_add_u64 v[158:159], v[158:159], 0, s[46:47]
	s_mov_b32 m0, s24
	ds_read_b128 v[196:199], v163 offset:49152
	ds_read_b128 v[200:203], v163 offset:50176
	ds_read_b128 v[216:219], v163 offset:51200
	ds_read_b128 v[220:223], v163 offset:52224
	ds_read_b128 v[224:227], v163 offset:53248
	ds_read_b128 v[228:231], v163 offset:54272
	ds_read_b128 v[232:235], v163 offset:55296
	ds_read_b128 v[236:239], v163 offset:56320
	global_load_lds_dwordx4 v[158:159], off
	s_add_i32 m0, s24, 0x2000
	s_add_u32 s22, s22, 0x40080
	v_lshl_add_u64 v[158:159], v[240:241], 0, s[46:47]
	s_addc_u32 s23, s23, 0
	s_add_i32 s24, s83, s34
	global_load_lds_dwordx4 v[158:159], off
	v_lshl_add_u64 v[158:159], s[22:23], 0, v[148:149]
	s_mov_b32 m0, s24
	s_nop 0
	global_load_lds_dwordx4 v[158:159], off
	v_lshl_add_u64 v[158:159], s[22:23], 0, v[152:153]
	s_add_i32 m0, s24, 0x2000
	s_nop 0
	global_load_lds_dwordx4 v[158:159], off
	v_lshl_add_u64 v[158:159], v[242:243], 0, s[46:47]
	s_mov_b32 m0, s39
	s_nop 0
	global_load_lds_dwordx4 v[158:159], off
	v_lshl_add_u64 v[158:159], v[244:245], 0, s[46:47]
	s_mov_b32 m0, s42
	s_nop 0
	global_load_lds_dwordx4 v[158:159], off
	s_waitcnt vmcnt(8)
	s_waitcnt lgkmcnt(0)
	s_barrier
	s_setprio 1
	s_waitcnt lgkmcnt(0)
	v_mfma_f32_16x16x32_bf16 v[78:81], v[164:167], v[196:199], v[78:81]
	v_mfma_f32_16x16x32_bf16 v[74:77], v[172:175], v[196:199], v[74:77]
	v_mfma_f32_16x16x32_bf16 v[62:65], v[164:167], v[216:219], v[62:65]
	v_mfma_f32_16x16x32_bf16 v[58:61], v[172:175], v[216:219], v[58:61]
	v_mfma_f32_16x16x32_bf16 v[46:49], v[164:167], v[224:227], v[46:49]
	v_mfma_f32_16x16x32_bf16 v[42:45], v[172:175], v[224:227], v[42:45]
	v_mfma_f32_16x16x32_bf16 v[30:33], v[164:167], v[232:235], v[30:33]
	v_mfma_f32_16x16x32_bf16 v[26:29], v[172:175], v[232:235], v[26:29]
	v_mfma_f32_16x16x32_bf16 v[78:81], v[168:171], v[200:203], v[78:81]
	v_mfma_f32_16x16x32_bf16 v[74:77], v[176:179], v[200:203], v[74:77]
	v_mfma_f32_16x16x32_bf16 v[62:65], v[168:171], v[220:223], v[62:65]
	v_mfma_f32_16x16x32_bf16 v[58:61], v[176:179], v[220:223], v[58:61]
	v_mfma_f32_16x16x32_bf16 v[46:49], v[168:171], v[228:231], v[46:49]
	v_mfma_f32_16x16x32_bf16 v[42:45], v[176:179], v[228:231], v[42:45]
	v_mfma_f32_16x16x32_bf16 v[30:33], v[168:171], v[236:239], v[30:33]
	v_mfma_f32_16x16x32_bf16 v[26:29], v[176:179], v[236:239], v[26:29]
	s_setprio 0
	s_setprio 1
	v_mfma_f32_16x16x32_bf16 v[70:73], v[180:183], v[196:199], v[70:73]
	v_mfma_f32_16x16x32_bf16 v[66:69], v[188:191], v[196:199], v[66:69]
	v_mfma_f32_16x16x32_bf16 v[54:57], v[180:183], v[216:219], v[54:57]
	v_mfma_f32_16x16x32_bf16 v[50:53], v[188:191], v[216:219], v[50:53]
	v_mfma_f32_16x16x32_bf16 v[38:41], v[180:183], v[224:227], v[38:41]
	v_mfma_f32_16x16x32_bf16 v[34:37], v[188:191], v[224:227], v[34:37]
	v_mfma_f32_16x16x32_bf16 v[22:25], v[180:183], v[232:235], v[22:25]
	v_mfma_f32_16x16x32_bf16 v[18:21], v[188:191], v[232:235], v[18:21]
	v_mfma_f32_16x16x32_bf16 v[70:73], v[184:187], v[200:203], v[70:73]
	v_mfma_f32_16x16x32_bf16 v[66:69], v[192:195], v[200:203], v[66:69]
	v_mfma_f32_16x16x32_bf16 v[54:57], v[184:187], v[220:223], v[54:57]
	v_mfma_f32_16x16x32_bf16 v[50:53], v[192:195], v[220:223], v[50:53]
	v_mfma_f32_16x16x32_bf16 v[38:41], v[184:187], v[228:231], v[38:41]
	v_mfma_f32_16x16x32_bf16 v[34:37], v[192:195], v[228:231], v[34:37]
	v_mfma_f32_16x16x32_bf16 v[22:25], v[184:187], v[236:239], v[22:25]
	v_mfma_f32_16x16x32_bf16 v[18:21], v[192:195], v[236:239], v[18:21]
	s_setprio 0
	s_barrier
	s_add_i32 s64, s64, 2
	s_add_u32 s20, s20, 0x100
	s_addc_u32 s21, s21, 0
	s_add_u32 s62, s62, 0x100
	s_addc_u32 s63, s63, 0

; #define PG8_STAGE(bufoff, gbase, voff) do { _Pragma("unroll") for (int _i = 0; _i < 2; ++_i) \
;         __builtin_amdgcn_global_load_lds((const unsigned*)((const char*)(gbase) + (voff)[_i]), (PG8_LAS unsigned*)(lds + (bufoff) + ldsw + _i * 8192), 16, 0, 0); } while (0)
; #define PG8_LDA(dst, b, h) do { _Pragma("unroll") for (int m = 0; m < 4; ++m) _Pragma("unroll") for (int k = 0; k < 2; ++k) dst[m][k] = *(const PG8_LAS bf16x8*)(lds + PG8_SA(b, h) + aoff + m * 2048 + k * 1024); } while (0)
; #define PG8_LDB(dst, b, h) do { _Pragma("unroll") for (int n = 0; n < 2; ++n) _Pragma("unroll") for (int k = 0; k < 2; ++k) dst[n][k] = *(const PG8_LAS bf16x8*)(lds + PG8_SB(b, h) + boff + n * 2048 + k * 1024); } while (0)
; #define PG8_MMA(ai, bj, At, Bt) do { __builtin_amdgcn_s_setprio(1); _Pragma("unroll") for (int m = 0; m < 4; ++m) _Pragma("unroll") for (int n = 0; n < 2; ++n) _Pragma("unroll") for (int k = 0; k < 2; ++k) \
;         acc[ai][bj][m][n] = __builtin_amdgcn_mfma_f32_16x16x32_bf16(Bt[n][k], At[m][k], acc[ai][bj][m][n], 0, 0, 0); __builtin_amdgcn_s_setprio(0); } while (0)
; #define PG8_WAIT_V(n) asm volatile("s_waitcnt vmcnt(" #n ")" ::: "memory")
; #define PG8_WAIT_L(n) asm volatile("s_waitcnt lgkmcnt(" #n ")" ::: "memory")
; #define PG8_BAR __builtin_amdgcn_s_barrier()
; #define PG8_SCHED __builtin_amdgcn_sched_barrier(0)
; template <class Epi, class Sched, bool ALIGN_EPI = false, bool SP2 = false>
; __device__ __forceinline__ void gemm_phase(PG8_LAS unsigned char* lds, const Gemm g, const Sched& S, const Epi& E) {
;     ...
;             const char* a1 = cA + (size_t)(t + 1) * kstep;
;             const char* a2 = last ? nA : cA + (size_t)(t + 2) * kstep; const char* b2 = last ? nB : cB + (size_t)(t + 2) * kstep;
;             const char* a3 = a2 + kstep; const char* b3 = b2 + kstep;
;             if (last && has_next) S.a_ready_inloop(nxt, ui + 1);
;             if constexpr (SP2) {
;             PG8_LDB(B0, 0, 0); PG8_LDB(B1, 0, 1); PG8_SCHED; PG8_LDA(At, 0, 0); PG8_STAGE(PG8_SA(1, 1), a1 + hstep, voffA);
;             PG8_WAIT_V(8); PG8_WAIT_L(0); PG8_BAR; PG8_MMA(0, 0, At, B0); PG8_MMA(0, 1, At, B1); PG8_BAR; PG8_SCHED;
;             PG8_LDA(At, 0, 1); PG8_STAGE(PG8_SB(0, 0), b2, voffB); PG8_STAGE(PG8_SB(0, 1), b2 + hstep, voffB); PG8_STAGE(PG8_SA(0, 0), a2, voffA);
.LBB0_211:
	s_mov_b64 s[18:19], s[6:7]
	s_mov_b64 s[20:21], s[14:15]
	s_and_b64 s[6:7], s[16:17], exec
	s_cselect_b32 s7, s37, s19
	s_cselect_b32 s6, s36, s18
	s_cselect_b32 s15, s3, s21
	s_cselect_b32 s14, s2, s20
	s_add_u32 s39, s20, 0x100
	s_addc_u32 s42, s21, 0
	s_mov_b32 s44, -2
	v_add_u32_e32 v142, s90, v188
	v_add_u32_e32 v172, s81, v188
	ds_read_b128 v[130:133], v142
	ds_read_b128 v[134:137], v142 offset:1024
	ds_read_b128 v[138:141], v142 offset:2048
	ds_read_b128 v[142:145], v142 offset:3072
	ds_read_b128 v[146:149], v172
	ds_read_b128 v[150:153], v172 offset:1024
	ds_read_b128 v[154:157], v172 offset:2048
	ds_read_b128 v[172:175], v172 offset:3072
	s_add_u32 s20, s18, 0x100
	s_addc_u32 s21, s19, 0
	s_cmp_eq_u32 s44, 40
	s_cselect_b32 s25, s7, s21
	s_cselect_b32 s24, s6, s20
	s_cselect_b32 s23, s15, s42
	s_cselect_b32 s22, s14, s39
	v_lshl_add_u64 v[202:203], s[18:19], 0, v[168:169]
	s_add_i32 m0, s27, 0xc000
	ds_read_b128 v[176:179], v189
	ds_read_b128 v[180:183], v189 offset:1024
	ds_read_b128 v[184:187], v189 offset:2048
	ds_read_b128 v[190:193], v189 offset:3072
	ds_read_b128 v[194:197], v189 offset:4096
	ds_read_b128 v[198:201], v189 offset:5120
	ds_read_b128 v[216:219], v189 offset:6144
	ds_read_b128 v[220:223], v189 offset:7168
	global_load_lds_dwordx4 v[202:203], off
	v_lshl_add_u64 v[202:203], s[18:19], 0, v[170:171]
	s_add_i32 m0, s27, 0xe000
	s_nop 0
	global_load_lds_dwordx4 v[202:203], off
	s_waitcnt vmcnt(8)
	s_waitcnt lgkmcnt(0)
	s_barrier
	s_setprio 1
	s_waitcnt lgkmcnt(0)
	v_mfma_f32_16x16x32_bf16 v[126:129], v[130:133], v[176:179], 0
	v_mfma_f32_16x16x32_bf16 v[122:125], v[138:141], v[176:179], 0
	v_mfma_f32_16x16x32_bf16 v[110:113], v[130:133], v[184:187], 0
	v_mfma_f32_16x16x32_bf16 v[106:109], v[138:141], v[184:187], 0
	v_mfma_f32_16x16x32_bf16 v[94:97], v[130:133], v[194:197], 0
	v_mfma_f32_16x16x32_bf16 v[90:93], v[138:141], v[194:197], 0
	v_mfma_f32_16x16x32_bf16 v[78:81], v[130:133], v[216:219], 0
	v_mfma_f32_16x16x32_bf16 v[74:77], v[138:141], v[216:219], 0
	v_mfma_f32_16x16x32_bf16 v[126:129], v[134:137], v[180:183], v[126:129]
	v_mfma_f32_16x16x32_bf16 v[122:125], v[142:145], v[180:183], v[122:125]
	v_mfma_f32_16x16x32_bf16 v[110:113], v[134:137], v[190:193], v[110:113]
	v_mfma_f32_16x16x32_bf16 v[106:109], v[142:145], v[190:193], v[106:109]
	v_mfma_f32_16x16x32_bf16 v[94:97], v[134:137], v[198:201], v[94:97]
	v_mfma_f32_16x16x32_bf16 v[90:93], v[142:145], v[198:201], v[90:93]
	v_mfma_f32_16x16x32_bf16 v[78:81], v[134:137], v[220:223], v[78:81]
	v_mfma_f32_16x16x32_bf16 v[74:77], v[142:145], v[220:223], v[74:77]
	s_setprio 0
	s_setprio 1
	v_mfma_f32_16x16x32_bf16 v[118:121], v[146:149], v[176:179], 0
	v_mfma_f32_16x16x32_bf16 v[114:117], v[154:157], v[176:179], 0
	v_mfma_f32_16x16x32_bf16 v[102:105], v[146:149], v[184:187], 0
	v_mfma_f32_16x16x32_bf16 v[98:101], v[154:157], v[184:187], 0
	v_mfma_f32_16x16x32_bf16 v[86:89], v[146:149], v[194:197], 0
	v_mfma_f32_16x16x32_bf16 v[82:85], v[154:157], v[194:197], 0
	v_mfma_f32_16x16x32_bf16 v[70:73], v[146:149], v[216:219], 0
	v_mfma_f32_16x16x32_bf16 v[66:69], v[154:157], v[216:219], 0
	v_mfma_f32_16x16x32_bf16 v[118:121], v[150:153], v[180:183], v[118:121]
	v_mfma_f32_16x16x32_bf16 v[114:117], v[172:175], v[180:183], v[114:117]
	v_mfma_f32_16x16x32_bf16 v[102:105], v[150:153], v[190:193], v[102:105]
	v_mfma_f32_16x16x32_bf16 v[98:101], v[172:175], v[190:193], v[98:101]
	v_mfma_f32_16x16x32_bf16 v[86:89], v[150:153], v[198:201], v[86:89]
	v_mfma_f32_16x16x32_bf16 v[82:85], v[172:175], v[198:201], v[82:85]
	v_mfma_f32_16x16x32_bf16 v[70:73], v[150:153], v[220:223], v[70:73]
	v_mfma_f32_16x16x32_bf16 v[66:69], v[172:175], v[220:223], v[66:69]
	s_setprio 0
	s_barrier
	s_add_i32 s18, s90, s26
	v_lshl_add_u64 v[202:203], s[22:23], 0, v[160:161]
	s_mov_b32 m0, s18
	ds_read_b128 v[176:179], v189 offset:16384
	ds_read_b128 v[180:183], v189 offset:17408
	ds_read_b128 v[184:187], v189 offset:18432
	ds_read_b128 v[190:193], v189 offset:19456
	ds_read_b128 v[194:197], v189 offset:20480
	ds_read_b128 v[198:201], v189 offset:21504
	ds_read_b128 v[216:219], v189 offset:22528
	ds_read_b128 v[220:223], v189 offset:23552
	global_load_lds_dwordx4 v[202:203], off
	s_add_i32 m0, s18, 0x2000
	s_add_u32 s18, s22, 0xb0000
	v_lshl_add_u64 v[224:225], s[22:23], 0, v[164:165]
	s_addc_u32 s19, s23, 0
	s_add_i32 s45, s81, s26
	global_load_lds_dwordx4 v[224:225], off
	v_lshl_add_u64 v[226:227], s[18:19], 0, v[160:161]
	s_mov_b32 m0, s45
	v_lshl_add_u64 v[228:229], s[24:25], 0, v[162:163]
	global_load_lds_dwordx4 v[226:227], off
	v_lshl_add_u64 v[226:227], s[18:19], 0, v[164:165]
	s_add_i32 m0, s45, 0x2000
	s_nop 0
	global_load_lds_dwordx4 v[226:227], off
	v_lshl_add_u64 v[226:227], s[24:25], 0, v[158:159]
	s_mov_b32 m0, s27
	s_nop 0
	global_load_lds_dwordx4 v[226:227], off
	s_mov_b32 m0, s28
	s_nop 0
	global_load_lds_dwordx4 v[228:229], off
	s_waitcnt vmcnt(8)
	s_waitcnt lgkmcnt(0)
	s_barrier
; #define PG8_STAGE(bufoff, gbase, voff) do { _Pragma("unroll") for (int _i = 0; _i < 2; ++_i) \
;         __builtin_amdgcn_global_load_lds((const unsigned*)((const char*)(gbase) + (voff)[_i]), (PG8_LAS unsigned*)(lds + (bufoff) + ldsw + _i * 8192), 16, 0, 0); } while (0)
; #define PG8_LDA(dst, b, h) do { _Pragma("unroll") for (int m = 0; m < 4; ++m) _Pragma("unroll") for (int k = 0; k < 2; ++k) dst[m][k] = *(const PG8_LAS bf16x8*)(lds + PG8_SA(b, h) + aoff + m * 2048 + k * 1024); } while (0)
; #define PG8_LDB(dst, b, h) do { _Pragma("unroll") for (int n = 0; n < 2; ++n) _Pragma("unroll") for (int k = 0; k < 2; ++k) dst[n][k] = *(const PG8_LAS bf16x8*)(lds + PG8_SB(b, h) + boff + n * 2048 + k * 1024); } while (0)
; #define PG8_MMA(ai, bj, At, Bt) do { __builtin_amdgcn_s_setprio(1); _Pragma("unroll") for (int m = 0; m < 4; ++m) _Pragma("unroll") for (int n = 0; n < 2; ++n) _Pragma("unroll") for (int k = 0; k < 2; ++k) \
;         acc[ai][bj][m][n] = __builtin_amdgcn_mfma_f32_16x16x32_bf16(Bt[n][k], At[m][k], acc[ai][bj][m][n], 0, 0, 0); __builtin_amdgcn_s_setprio(0); } while (0)
; #define PG8_WAIT_V(n) asm volatile("s_waitcnt vmcnt(" #n ")" ::: "memory")
; #define PG8_WAIT_L(n) asm volatile("s_waitcnt lgkmcnt(" #n ")" ::: "memory")
; #define PG8_BAR __builtin_amdgcn_s_barrier()
; #define PG8_SCHED __builtin_amdgcn_sched_barrier(0)
; template <class Epi, class Sched, bool ALIGN_EPI = false, bool SP2 = false>
; __device__ __forceinline__ void gemm_phase(PG8_LAS unsigned char* lds, const Gemm g, const Sched& S, const Epi& E) {
;     ...
;             PG8_WAIT_V(8); PG8_WAIT_L(0); PG8_BAR; PG8_MMA(1, 0, At, B0); PG8_MMA(1, 1, At, B1); PG8_BAR; PG8_SCHED;
;             PG8_LDB(B0, 1, 0); PG8_LDB(B1, 1, 1); PG8_SCHED; PG8_LDA(At, 1, 0); PG8_STAGE(PG8_SA(0, 1), a2 + hstep, voffA);
;             PG8_WAIT_V(8); PG8_WAIT_L(0); PG8_BAR; PG8_MMA(0, 0, At, B0); PG8_MMA(0, 1, At, B1); PG8_BAR; PG8_SCHED;
	s_setprio 1
	s_waitcnt lgkmcnt(0)
	v_mfma_f32_16x16x32_bf16 v[62:65], v[130:133], v[176:179], 0
	v_mfma_f32_16x16x32_bf16 v[58:61], v[138:141], v[176:179], 0
	v_mfma_f32_16x16x32_bf16 v[46:49], v[130:133], v[184:187], 0
	v_mfma_f32_16x16x32_bf16 v[42:45], v[138:141], v[184:187], 0
	v_mfma_f32_16x16x32_bf16 v[30:33], v[130:133], v[194:197], 0
	v_mfma_f32_16x16x32_bf16 v[26:29], v[138:141], v[194:197], 0
	v_mfma_f32_16x16x32_bf16 v[14:17], v[130:133], v[216:219], 0
	v_mfma_f32_16x16x32_bf16 v[10:13], v[138:141], v[216:219], 0
	v_mfma_f32_16x16x32_bf16 v[62:65], v[134:137], v[180:183], v[62:65]
	v_mfma_f32_16x16x32_bf16 v[58:61], v[142:145], v[180:183], v[58:61]
	v_mfma_f32_16x16x32_bf16 v[46:49], v[134:137], v[190:193], v[46:49]
	v_mfma_f32_16x16x32_bf16 v[42:45], v[142:145], v[190:193], v[42:45]
	v_mfma_f32_16x16x32_bf16 v[30:33], v[134:137], v[198:201], v[30:33]
	v_mfma_f32_16x16x32_bf16 v[26:29], v[142:145], v[198:201], v[26:29]
	v_mfma_f32_16x16x32_bf16 v[14:17], v[134:137], v[220:223], v[14:17]
	v_mfma_f32_16x16x32_bf16 v[10:13], v[142:145], v[220:223], v[10:13]
	s_setprio 0
	s_setprio 1
	v_mfma_f32_16x16x32_bf16 v[54:57], v[146:149], v[176:179], 0
	v_mfma_f32_16x16x32_bf16 v[50:53], v[154:157], v[176:179], 0
	v_mfma_f32_16x16x32_bf16 v[38:41], v[146:149], v[184:187], 0
	v_mfma_f32_16x16x32_bf16 v[34:37], v[154:157], v[184:187], 0
	v_mfma_f32_16x16x32_bf16 v[22:25], v[146:149], v[194:197], 0
	v_mfma_f32_16x16x32_bf16 v[18:21], v[154:157], v[194:197], 0
	v_mfma_f32_16x16x32_bf16 v[6:9], v[146:149], v[216:219], 0
	v_mfma_f32_16x16x32_bf16 v[2:5], v[154:157], v[216:219], 0
	v_mfma_f32_16x16x32_bf16 v[54:57], v[150:153], v[180:183], v[54:57]
	v_mfma_f32_16x16x32_bf16 v[50:53], v[172:175], v[180:183], v[50:53]
	v_mfma_f32_16x16x32_bf16 v[38:41], v[150:153], v[190:193], v[38:41]
	v_mfma_f32_16x16x32_bf16 v[34:37], v[172:175], v[190:193], v[34:37]
	v_mfma_f32_16x16x32_bf16 v[22:25], v[150:153], v[198:201], v[22:25]
	v_mfma_f32_16x16x32_bf16 v[18:21], v[172:175], v[198:201], v[18:21]
	v_mfma_f32_16x16x32_bf16 v[6:9], v[150:153], v[220:223], v[6:9]
	v_mfma_f32_16x16x32_bf16 v[2:5], v[172:175], v[220:223], v[2:5]
	s_setprio 0
	s_barrier
	v_add_u32_e32 v142, s82, v188
	v_add_u32_e32 v172, s83, v188
	ds_read_b128 v[130:133], v142
	ds_read_b128 v[134:137], v142 offset:1024
	ds_read_b128 v[138:141], v142 offset:2048
	ds_read_b128 v[142:145], v142 offset:3072
	ds_read_b128 v[146:149], v172
	ds_read_b128 v[150:153], v172 offset:1024
	ds_read_b128 v[154:157], v172 offset:2048
	ds_read_b128 v[172:175], v172 offset:3072
	s_add_u32 s18, s24, 0xb0000
	s_addc_u32 s19, s25, 0
	s_mov_b32 m0, s29
	v_lshl_add_u64 v[230:231], s[18:19], 0, v[158:159]
	ds_read_b128 v[176:179], v189 offset:32768
	ds_read_b128 v[180:183], v189 offset:33792
	ds_read_b128 v[184:187], v189 offset:34816
	ds_read_b128 v[190:193], v189 offset:35840
	ds_read_b128 v[194:197], v189 offset:36864
	ds_read_b128 v[198:201], v189 offset:37888
	ds_read_b128 v[216:219], v189 offset:38912
	ds_read_b128 v[220:223], v189 offset:39936
	global_load_lds_dwordx4 v[230:231], off
	v_lshl_add_u64 v[230:231], s[18:19], 0, v[162:163]
	s_mov_b32 m0, s30
	s_nop 0
	global_load_lds_dwordx4 v[230:231], off
	s_waitcnt vmcnt(8)
	s_waitcnt lgkmcnt(0)
	s_barrier
	s_setprio 1
	s_waitcnt lgkmcnt(0)
	v_mfma_f32_16x16x32_bf16 v[126:129], v[130:133], v[176:179], v[126:129]
	v_mfma_f32_16x16x32_bf16 v[122:125], v[138:141], v[176:179], v[122:125]
	v_mfma_f32_16x16x32_bf16 v[110:113], v[130:133], v[184:187], v[110:113]
	v_mfma_f32_16x16x32_bf16 v[106:109], v[138:141], v[184:187], v[106:109]
	v_mfma_f32_16x16x32_bf16 v[94:97], v[130:133], v[194:197], v[94:97]
	v_mfma_f32_16x16x32_bf16 v[90:93], v[138:141], v[194:197], v[90:93]
	v_mfma_f32_16x16x32_bf16 v[78:81], v[130:133], v[216:219], v[78:81]
	v_mfma_f32_16x16x32_bf16 v[74:77], v[138:141], v[216:219], v[74:77]
	v_mfma_f32_16x16x32_bf16 v[126:129], v[134:137], v[180:183], v[126:129]
	v_mfma_f32_16x16x32_bf16 v[122:125], v[142:145], v[180:183], v[122:125]
	v_mfma_f32_16x16x32_bf16 v[110:113], v[134:137], v[190:193], v[110:113]
	v_mfma_f32_16x16x32_bf16 v[106:109], v[142:145], v[190:193], v[106:109]
	v_mfma_f32_16x16x32_bf16 v[94:97], v[134:137], v[198:201], v[94:97]
	v_mfma_f32_16x16x32_bf16 v[90:93], v[142:145], v[198:201], v[90:93]
	v_mfma_f32_16x16x32_bf16 v[78:81], v[134:137], v[220:223], v[78:81]
	v_mfma_f32_16x16x32_bf16 v[74:77], v[142:145], v[220:223], v[74:77]
	s_setprio 0
	s_setprio 1
	v_mfma_f32_16x16x32_bf16 v[118:121], v[146:149], v[176:179], v[118:121]
	v_mfma_f32_16x16x32_bf16 v[114:117], v[154:157], v[176:179], v[114:117]
	v_mfma_f32_16x16x32_bf16 v[102:105], v[146:149], v[184:187], v[102:105]
	v_mfma_f32_16x16x32_bf16 v[98:101], v[154:157], v[184:187], v[98:101]
	v_mfma_f32_16x16x32_bf16 v[86:89], v[146:149], v[194:197], v[86:89]
	v_mfma_f32_16x16x32_bf16 v[82:85], v[154:157], v[194:197], v[82:85]
	v_mfma_f32_16x16x32_bf16 v[70:73], v[146:149], v[216:219], v[70:73]
	v_mfma_f32_16x16x32_bf16 v[66:69], v[154:157], v[216:219], v[66:69]
	v_mfma_f32_16x16x32_bf16 v[118:121], v[150:153], v[180:183], v[118:121]
	v_mfma_f32_16x16x32_bf16 v[114:117], v[172:175], v[180:183], v[114:117]
	v_mfma_f32_16x16x32_bf16 v[102:105], v[150:153], v[190:193], v[102:105]
	v_mfma_f32_16x16x32_bf16 v[98:101], v[172:175], v[190:193], v[98:101]
	v_mfma_f32_16x16x32_bf16 v[86:89], v[150:153], v[198:201], v[86:89]
	v_mfma_f32_16x16x32_bf16 v[82:85], v[172:175], v[198:201], v[82:85]
	v_mfma_f32_16x16x32_bf16 v[70:73], v[150:153], v[220:223], v[70:73]
	v_mfma_f32_16x16x32_bf16 v[66:69], v[172:175], v[220:223], v[66:69]
	s_setprio 0
	s_barrier
; #define PG8_STAGE(bufoff, gbase, voff) do { _Pragma("unroll") for (int _i = 0; _i < 2; ++_i) \
;         __builtin_amdgcn_global_load_lds((const unsigned*)((const char*)(gbase) + (voff)[_i]), (PG8_LAS unsigned*)(lds + (bufoff) + ldsw + _i * 8192), 16, 0, 0); } while (0)
; #define PG8_LDA(dst, b, h) do { _Pragma("unroll") for (int m = 0; m < 4; ++m) _Pragma("unroll") for (int k = 0; k < 2; ++k) dst[m][k] = *(const PG8_LAS bf16x8*)(lds + PG8_SA(b, h) + aoff + m * 2048 + k * 1024); } while (0)
; #define PG8_MMA(ai, bj, At, Bt) do { __builtin_amdgcn_s_setprio(1); _Pragma("unroll") for (int m = 0; m < 4; ++m) _Pragma("unroll") for (int n = 0; n < 2; ++n) _Pragma("unroll") for (int k = 0; k < 2; ++k) \
;         acc[ai][bj][m][n] = __builtin_amdgcn_mfma_f32_16x16x32_bf16(Bt[n][k], At[m][k], acc[ai][bj][m][n], 0, 0, 0); __builtin_amdgcn_s_setprio(0); } while (0)
; #define PG8_WAIT_V(n) asm volatile("s_waitcnt vmcnt(" #n ")" ::: "memory")
; #define PG8_WAIT_L(n) asm volatile("s_waitcnt lgkmcnt(" #n ")" ::: "memory")
; #define PG8_BAR __builtin_amdgcn_s_barrier()
; #define PG8_SCHED __builtin_amdgcn_sched_barrier(0)
; template <class Epi, class Sched, bool ALIGN_EPI = false, bool SP2 = false>
; __device__ __forceinline__ void gemm_phase(PG8_LAS unsigned char* lds, const Gemm g, const Sched& S, const Epi& E) {
;     ...
;             PG8_WAIT_V(8); PG8_WAIT_L(0); PG8_BAR; PG8_MMA(0, 0, At, B0); PG8_MMA(0, 1, At, B1); PG8_BAR; PG8_SCHED;
;             PG8_LDA(At, 1, 1); PG8_STAGE(PG8_SB(1, 0), b3, voffB); PG8_STAGE(PG8_SB(1, 1), b3 + hstep, voffB); PG8_STAGE(PG8_SA(1, 0), a3, voffA);
;             PG8_WAIT_V(8); PG8_WAIT_L(0); PG8_BAR; PG8_MMA(1, 0, At, B0); PG8_MMA(1, 1, At, B1); PG8_BAR; PG8_SCHED;
	s_add_i32 s18, s82, s26
	v_lshl_add_u64 v[202:203], v[202:203], 0, s[46:47]
	s_mov_b32 m0, s18
	ds_read_b128 v[176:179], v189 offset:49152
	ds_read_b128 v[180:183], v189 offset:50176
	ds_read_b128 v[184:187], v189 offset:51200
	ds_read_b128 v[190:193], v189 offset:52224
	ds_read_b128 v[194:197], v189 offset:53248
	ds_read_b128 v[198:201], v189 offset:54272
	ds_read_b128 v[216:219], v189 offset:55296
	ds_read_b128 v[220:223], v189 offset:56320
	global_load_lds_dwordx4 v[202:203], off
	s_add_i32 m0, s18, 0x2000
	s_add_u32 s18, s22, 0xb0080
	v_lshl_add_u64 v[202:203], v[224:225], 0, s[46:47]
	s_addc_u32 s19, s23, 0
	s_add_i32 s22, s83, s26
	global_load_lds_dwordx4 v[202:203], off
	v_lshl_add_u64 v[202:203], s[18:19], 0, v[160:161]
	s_mov_b32 m0, s22
	s_nop 0
	global_load_lds_dwordx4 v[202:203], off
	v_lshl_add_u64 v[202:203], s[18:19], 0, v[164:165]
	s_add_i32 m0, s22, 0x2000
	s_nop 0
	global_load_lds_dwordx4 v[202:203], off
	v_lshl_add_u64 v[202:203], v[226:227], 0, s[46:47]
	s_mov_b32 m0, s31
	s_nop 0
	global_load_lds_dwordx4 v[202:203], off
	v_lshl_add_u64 v[202:203], v[228:229], 0, s[46:47]
	s_mov_b32 m0, s34
	s_nop 0
	global_load_lds_dwordx4 v[202:203], off
	s_waitcnt vmcnt(8)
	s_waitcnt lgkmcnt(0)
	s_barrier
	s_setprio 1
	s_waitcnt lgkmcnt(0)
	v_mfma_f32_16x16x32_bf16 v[62:65], v[130:133], v[176:179], v[62:65]
	v_mfma_f32_16x16x32_bf16 v[58:61], v[138:141], v[176:179], v[58:61]
	v_mfma_f32_16x16x32_bf16 v[46:49], v[130:133], v[184:187], v[46:49]
	v_mfma_f32_16x16x32_bf16 v[42:45], v[138:141], v[184:187], v[42:45]
	v_mfma_f32_16x16x32_bf16 v[30:33], v[130:133], v[194:197], v[30:33]
	v_mfma_f32_16x16x32_bf16 v[26:29], v[138:141], v[194:197], v[26:29]
	v_mfma_f32_16x16x32_bf16 v[14:17], v[130:133], v[216:219], v[14:17]
	v_mfma_f32_16x16x32_bf16 v[10:13], v[138:141], v[216:219], v[10:13]
	v_mfma_f32_16x16x32_bf16 v[62:65], v[134:137], v[180:183], v[62:65]
	v_mfma_f32_16x16x32_bf16 v[58:61], v[142:145], v[180:183], v[58:61]
	v_mfma_f32_16x16x32_bf16 v[46:49], v[134:137], v[190:193], v[46:49]
	v_mfma_f32_16x16x32_bf16 v[42:45], v[142:145], v[190:193], v[42:45]
	v_mfma_f32_16x16x32_bf16 v[30:33], v[134:137], v[198:201], v[30:33]
	v_mfma_f32_16x16x32_bf16 v[26:29], v[142:145], v[198:201], v[26:29]
	v_mfma_f32_16x16x32_bf16 v[14:17], v[134:137], v[220:223], v[14:17]
	v_mfma_f32_16x16x32_bf16 v[10:13], v[142:145], v[220:223], v[10:13]
	s_setprio 0
	s_setprio 1
	v_mfma_f32_16x16x32_bf16 v[54:57], v[146:149], v[176:179], v[54:57]
	v_mfma_f32_16x16x32_bf16 v[50:53], v[154:157], v[176:179], v[50:53]
	v_mfma_f32_16x16x32_bf16 v[38:41], v[146:149], v[184:187], v[38:41]
	v_mfma_f32_16x16x32_bf16 v[34:37], v[154:157], v[184:187], v[34:37]
	v_mfma_f32_16x16x32_bf16 v[22:25], v[146:149], v[194:197], v[22:25]
	v_mfma_f32_16x16x32_bf16 v[18:21], v[154:157], v[194:197], v[18:21]
	v_mfma_f32_16x16x32_bf16 v[6:9], v[146:149], v[216:219], v[6:9]
	v_mfma_f32_16x16x32_bf16 v[2:5], v[154:157], v[216:219], v[2:5]
	v_mfma_f32_16x16x32_bf16 v[54:57], v[150:153], v[180:183], v[54:57]
	v_mfma_f32_16x16x32_bf16 v[50:53], v[172:175], v[180:183], v[50:53]
	v_mfma_f32_16x16x32_bf16 v[38:41], v[150:153], v[190:193], v[38:41]
	v_mfma_f32_16x16x32_bf16 v[34:37], v[172:175], v[190:193], v[34:37]
	v_mfma_f32_16x16x32_bf16 v[22:25], v[150:153], v[198:201], v[22:25]
	v_mfma_f32_16x16x32_bf16 v[18:21], v[172:175], v[198:201], v[18:21]
	v_mfma_f32_16x16x32_bf16 v[6:9], v[150:153], v[220:223], v[6:9]
	v_mfma_f32_16x16x32_bf16 v[2:5], v[172:175], v[220:223], v[2:5]
	s_setprio 0
	s_barrier
	s_add_i32 s44, s44, 2
	s_add_u32 s39, s39, 0x100
	s_addc_u32 s42, s42, 0
	s_mov_b64 s[18:19], s[20:21]

; #define PG8_STAGE(bufoff, gbase, voff) do { _Pragma("unroll") for (int _i = 0; _i < 2; ++_i) \
;         __builtin_amdgcn_global_load_lds((const unsigned*)((const char*)(gbase) + (voff)[_i]), (PG8_LAS unsigned*)(lds + (bufoff) + ldsw + _i * 8192), 16, 0, 0); } while (0)
; #define PG8_LDA(dst, b, h) do { _Pragma("unroll") for (int m = 0; m < 4; ++m) _Pragma("unroll") for (int k = 0; k < 2; ++k) dst[m][k] = *(const PG8_LAS bf16x8*)(lds + PG8_SA(b, h) + aoff + m * 2048 + k * 1024); } while (0)
; #define PG8_LDB(dst, b, h) do { _Pragma("unroll") for (int n = 0; n < 2; ++n) _Pragma("unroll") for (int k = 0; k < 2; ++k) dst[n][k] = *(const PG8_LAS bf16x8*)(lds + PG8_SB(b, h) + boff + n * 2048 + k * 1024); } while (0)
; #define PG8_MMA(ai, bj, At, Bt) do { __builtin_amdgcn_s_setprio(1); _Pragma("unroll") for (int m = 0; m < 4; ++m) _Pragma("unroll") for (int n = 0; n < 2; ++n) _Pragma("unroll") for (int k = 0; k < 2; ++k) \
;         acc[ai][bj][m][n] = __builtin_amdgcn_mfma_f32_16x16x32_bf16(Bt[n][k], At[m][k], acc[ai][bj][m][n], 0, 0, 0); __builtin_amdgcn_s_setprio(0); } while (0)
; #define PG8_WAIT_V(n) asm volatile("s_waitcnt vmcnt(" #n ")" ::: "memory")
; #define PG8_WAIT_L(n) asm volatile("s_waitcnt lgkmcnt(" #n ")" ::: "memory")
; #define PG8_BAR __builtin_amdgcn_s_barrier()
; #define PG8_SCHED __builtin_amdgcn_sched_barrier(0)
; template <class Epi, class Sched, bool ALIGN_EPI = false, bool SP2 = false>
; __device__ __forceinline__ void gemm_phase(PG8_LAS unsigned char* lds, const Gemm g, const Sched& S, const Epi& E) {
;     ...
;             const char* a1 = cA + (size_t)(t + 1) * kstep;
;             const char* a2 = last ? nA : cA + (size_t)(t + 2) * kstep; const char* b2 = last ? nB : cB + (size_t)(t + 2) * kstep;
;             const char* a3 = a2 + kstep; const char* b3 = b2 + kstep;
;             if (last && has_next) S.a_ready_inloop(nxt, ui + 1);
;             if constexpr (SP2) {
;             PG8_LDB(B0, 0, 0); PG8_LDB(B1, 0, 1); PG8_SCHED; PG8_LDA(At, 0, 0); PG8_STAGE(PG8_SA(1, 1), a1 + hstep, voffA);
;             PG8_WAIT_V(8); PG8_WAIT_L(0); PG8_BAR; PG8_MMA(0, 0, At, B0); PG8_MMA(0, 1, At, B1); PG8_BAR; PG8_SCHED;
;             PG8_LDA(At, 0, 1); PG8_STAGE(PG8_SB(0, 0), b2, voffB); PG8_STAGE(PG8_SB(0, 1), b2 + hstep, voffB); PG8_STAGE(PG8_SA(0, 0), a2, voffA);
.LBB0_318:
	s_ashr_i32 s17, s16, 31
	s_lshl_b64 s[20:21], s[16:17], 19
	s_add_u32 s20, s34, s20
	s_addc_u32 s21, s35, s21
	s_and_b64 s[22:23], s[2:3], exec
	s_cselect_b32 s13, s21, s25
	s_cselect_b32 s17, s20, s24
	s_ashr_i32 s19, s18, 31
	s_lshl_b64 s[22:23], s[18:19], 19
	s_add_u32 s22, s36, s22
	s_addc_u32 s23, s37, s23
	s_and_b64 s[28:29], s[2:3], exec
	s_cselect_b32 s19, s23, s27
	s_cselect_b32 s42, s22, s26
	s_add_u32 s24, s24, 0x40080
	s_addc_u32 s25, s25, 0
	s_add_u32 s44, s26, 0x100
	s_addc_u32 s45, s27, 0
	s_mov_b32 s52, -2
	v_add_u32_e32 v158, s90, v200
	v_add_u32_e32 v174, s81, v200
	ds_read_b128 v[146:149], v158
	ds_read_b128 v[150:153], v158 offset:1024
	ds_read_b128 v[154:157], v158 offset:2048
	ds_read_b128 v[158:161], v158 offset:3072
	ds_read_b128 v[162:165], v174
	ds_read_b128 v[166:169], v174 offset:1024
	ds_read_b128 v[170:173], v174 offset:2048
	ds_read_b128 v[174:177], v174 offset:3072
	s_add_u32 s26, s24, 0xfffc0080
	s_addc_u32 s27, s25, -1
	s_cmp_eq_u32 s52, 12
	s_cselect_b32 s29, s13, s27
	s_cselect_b32 s28, s17, s26
	s_cselect_b32 s27, s19, s45
	s_cselect_b32 s26, s42, s44
	v_lshl_add_u64 v[198:199], s[24:25], 0, v[190:191]
	s_add_i32 m0, s39, 0xc000
	ds_read_b128 v[216:219], v202
	ds_read_b128 v[220:223], v202 offset:1024
	ds_read_b128 v[224:227], v202 offset:2048
	ds_read_b128 v[228:231], v202 offset:3072
	ds_read_b128 v[232:235], v202 offset:4096
	ds_read_b128 v[236:239], v202 offset:5120
	ds_read_b128 v[240:243], v202 offset:6144
	ds_read_b128 v[244:247], v202 offset:7168
	global_load_lds_dwordx4 v[198:199], off
	v_lshl_add_u64 v[198:199], s[24:25], 0, v[192:193]
	s_add_i32 m0, s39, 0xe000
	s_nop 0
	global_load_lds_dwordx4 v[198:199], off
	s_waitcnt vmcnt(8)
	s_waitcnt lgkmcnt(0)
	s_barrier
	s_setprio 1
	s_waitcnt lgkmcnt(0)
	v_mfma_f32_16x16x32_bf16 v[142:145], v[146:149], v[216:219], 0
	v_mfma_f32_16x16x32_bf16 v[138:141], v[154:157], v[216:219], 0
	v_mfma_f32_16x16x32_bf16 v[126:129], v[146:149], v[224:227], 0
	v_mfma_f32_16x16x32_bf16 v[122:125], v[154:157], v[224:227], 0
	v_mfma_f32_16x16x32_bf16 v[110:113], v[146:149], v[232:235], 0
	v_mfma_f32_16x16x32_bf16 v[106:109], v[154:157], v[232:235], 0
	v_mfma_f32_16x16x32_bf16 v[94:97], v[146:149], v[240:243], 0
	v_mfma_f32_16x16x32_bf16 v[90:93], v[154:157], v[240:243], 0
	v_mfma_f32_16x16x32_bf16 v[142:145], v[150:153], v[220:223], v[142:145]
	v_mfma_f32_16x16x32_bf16 v[138:141], v[158:161], v[220:223], v[138:141]
	v_mfma_f32_16x16x32_bf16 v[126:129], v[150:153], v[228:231], v[126:129]
	v_mfma_f32_16x16x32_bf16 v[122:125], v[158:161], v[228:231], v[122:125]
	v_mfma_f32_16x16x32_bf16 v[110:113], v[150:153], v[236:239], v[110:113]
	v_mfma_f32_16x16x32_bf16 v[106:109], v[158:161], v[236:239], v[106:109]
	v_mfma_f32_16x16x32_bf16 v[94:97], v[150:153], v[244:247], v[94:97]
	v_mfma_f32_16x16x32_bf16 v[90:93], v[158:161], v[244:247], v[90:93]
	s_setprio 0
	s_setprio 1
	v_mfma_f32_16x16x32_bf16 v[134:137], v[162:165], v[216:219], 0
	v_mfma_f32_16x16x32_bf16 v[130:133], v[170:173], v[216:219], 0
	v_mfma_f32_16x16x32_bf16 v[118:121], v[162:165], v[224:227], 0
	v_mfma_f32_16x16x32_bf16 v[114:117], v[170:173], v[224:227], 0
	v_mfma_f32_16x16x32_bf16 v[102:105], v[162:165], v[232:235], 0
	v_mfma_f32_16x16x32_bf16 v[98:101], v[170:173], v[232:235], 0
	v_mfma_f32_16x16x32_bf16 v[86:89], v[162:165], v[240:243], 0
	v_mfma_f32_16x16x32_bf16 v[82:85], v[170:173], v[240:243], 0
	v_mfma_f32_16x16x32_bf16 v[134:137], v[166:169], v[220:223], v[134:137]
	v_mfma_f32_16x16x32_bf16 v[130:133], v[174:177], v[220:223], v[130:133]
	v_mfma_f32_16x16x32_bf16 v[118:121], v[166:169], v[228:231], v[118:121]
	v_mfma_f32_16x16x32_bf16 v[114:117], v[174:177], v[228:231], v[114:117]
	v_mfma_f32_16x16x32_bf16 v[102:105], v[166:169], v[236:239], v[102:105]
	v_mfma_f32_16x16x32_bf16 v[98:101], v[174:177], v[236:239], v[98:101]
	v_mfma_f32_16x16x32_bf16 v[86:89], v[166:169], v[244:247], v[86:89]
	v_mfma_f32_16x16x32_bf16 v[82:85], v[174:177], v[244:247], v[82:85]
	s_setprio 0
	s_barrier
	s_add_i32 s53, s90, s38
	v_lshl_add_u64 v[198:199], s[26:27], 0, v[180:181]
	s_mov_b32 m0, s53
	ds_read_b128 v[216:219], v202 offset:16384
	ds_read_b128 v[220:223], v202 offset:17408
	ds_read_b128 v[224:227], v202 offset:18432
	ds_read_b128 v[228:231], v202 offset:19456
	ds_read_b128 v[232:235], v202 offset:20480
	ds_read_b128 v[236:239], v202 offset:21504
	ds_read_b128 v[240:243], v202 offset:22528
	ds_read_b128 v[244:247], v202 offset:23552
	global_load_lds_dwordx4 v[198:199], off
	s_add_i32 m0, s53, 0x2000
	s_add_u32 vcc_lo, s26, 0x40000
	v_lshl_add_u64 v[248:249], s[26:27], 0, v[184:185]
	s_addc_u32 vcc_hi, s27, 0
	s_add_i32 s53, s81, s38
	global_load_lds_dwordx4 v[248:249], off
	v_lshl_add_u64 v[250:251], vcc, 0, v[180:181]
	s_mov_b32 m0, s53
	v_lshl_add_u64 v[252:253], s[28:29], 0, v[182:183]
	global_load_lds_dwordx4 v[250:251], off
	v_lshl_add_u64 v[250:251], vcc, 0, v[184:185]
	s_add_i32 m0, s53, 0x2000
	s_nop 0
	global_load_lds_dwordx4 v[250:251], off
	v_lshl_add_u64 v[250:251], s[28:29], 0, v[178:179]
	s_mov_b32 m0, s39
	s_nop 0
	global_load_lds_dwordx4 v[250:251], off
	s_mov_b32 m0, s60
	s_nop 0
	global_load_lds_dwordx4 v[252:253], off
	s_waitcnt vmcnt(8)
	s_waitcnt lgkmcnt(0)
	s_barrier
; #define PG8_STAGE(bufoff, gbase, voff) do { _Pragma("unroll") for (int _i = 0; _i < 2; ++_i) \
;         __builtin_amdgcn_global_load_lds((const unsigned*)((const char*)(gbase) + (voff)[_i]), (PG8_LAS unsigned*)(lds + (bufoff) + ldsw + _i * 8192), 16, 0, 0); } while (0)
; #define PG8_LDA(dst, b, h) do { _Pragma("unroll") for (int m = 0; m < 4; ++m) _Pragma("unroll") for (int k = 0; k < 2; ++k) dst[m][k] = *(const PG8_LAS bf16x8*)(lds + PG8_SA(b, h) + aoff + m * 2048 + k * 1024); } while (0)
; #define PG8_LDB(dst, b, h) do { _Pragma("unroll") for (int n = 0; n < 2; ++n) _Pragma("unroll") for (int k = 0; k < 2; ++k) dst[n][k] = *(const PG8_LAS bf16x8*)(lds + PG8_SB(b, h) + boff + n * 2048 + k * 1024); } while (0)
; #define PG8_MMA(ai, bj, At, Bt) do { __builtin_amdgcn_s_setprio(1); _Pragma("unroll") for (int m = 0; m < 4; ++m) _Pragma("unroll") for (int n = 0; n < 2; ++n) _Pragma("unroll") for (int k = 0; k < 2; ++k) \
;         acc[ai][bj][m][n] = __builtin_amdgcn_mfma_f32_16x16x32_bf16(Bt[n][k], At[m][k], acc[ai][bj][m][n], 0, 0, 0); __builtin_amdgcn_s_setprio(0); } while (0)
; #define PG8_WAIT_V(n) asm volatile("s_waitcnt vmcnt(" #n ")" ::: "memory")
; #define PG8_WAIT_L(n) asm volatile("s_waitcnt lgkmcnt(" #n ")" ::: "memory")
; #define PG8_BAR __builtin_amdgcn_s_barrier()
; #define PG8_SCHED __builtin_amdgcn_sched_barrier(0)
; template <class Epi, class Sched, bool ALIGN_EPI = false, bool SP2 = false>
; __device__ __forceinline__ void gemm_phase(PG8_LAS unsigned char* lds, const Gemm g, const Sched& S, const Epi& E) {
;     ...
;             PG8_WAIT_V(8); PG8_WAIT_L(0); PG8_BAR; PG8_MMA(1, 0, At, B0); PG8_MMA(1, 1, At, B1); PG8_BAR; PG8_SCHED;
;             PG8_LDB(B0, 1, 0); PG8_LDB(B1, 1, 1); PG8_SCHED; PG8_LDA(At, 1, 0); PG8_STAGE(PG8_SA(0, 1), a2 + hstep, voffA);
;             PG8_WAIT_V(8); PG8_WAIT_L(0); PG8_BAR; PG8_MMA(0, 0, At, B0); PG8_MMA(0, 1, At, B1); PG8_BAR; PG8_SCHED;
	s_setprio 1
	s_waitcnt lgkmcnt(0)
	v_mfma_f32_16x16x32_bf16 v[78:81], v[146:149], v[216:219], 0
	v_mfma_f32_16x16x32_bf16 v[74:77], v[154:157], v[216:219], 0
	v_mfma_f32_16x16x32_bf16 v[62:65], v[146:149], v[224:227], 0
	v_mfma_f32_16x16x32_bf16 v[58:61], v[154:157], v[224:227], 0
	v_mfma_f32_16x16x32_bf16 v[46:49], v[146:149], v[232:235], 0
	v_mfma_f32_16x16x32_bf16 v[42:45], v[154:157], v[232:235], 0
	v_mfma_f32_16x16x32_bf16 v[30:33], v[146:149], v[240:243], 0
	v_mfma_f32_16x16x32_bf16 v[26:29], v[154:157], v[240:243], 0
	v_mfma_f32_16x16x32_bf16 v[78:81], v[150:153], v[220:223], v[78:81]
	v_mfma_f32_16x16x32_bf16 v[74:77], v[158:161], v[220:223], v[74:77]
	v_mfma_f32_16x16x32_bf16 v[62:65], v[150:153], v[228:231], v[62:65]
	v_mfma_f32_16x16x32_bf16 v[58:61], v[158:161], v[228:231], v[58:61]
	v_mfma_f32_16x16x32_bf16 v[46:49], v[150:153], v[236:239], v[46:49]
	v_mfma_f32_16x16x32_bf16 v[42:45], v[158:161], v[236:239], v[42:45]
	v_mfma_f32_16x16x32_bf16 v[30:33], v[150:153], v[244:247], v[30:33]
	v_mfma_f32_16x16x32_bf16 v[26:29], v[158:161], v[244:247], v[26:29]
	s_setprio 0
	s_setprio 1
	v_mfma_f32_16x16x32_bf16 v[70:73], v[162:165], v[216:219], 0
	v_mfma_f32_16x16x32_bf16 v[66:69], v[170:173], v[216:219], 0
	v_mfma_f32_16x16x32_bf16 v[54:57], v[162:165], v[224:227], 0
	v_mfma_f32_16x16x32_bf16 v[50:53], v[170:173], v[224:227], 0
	v_mfma_f32_16x16x32_bf16 v[38:41], v[162:165], v[232:235], 0
	v_mfma_f32_16x16x32_bf16 v[34:37], v[170:173], v[232:235], 0
	v_mfma_f32_16x16x32_bf16 v[22:25], v[162:165], v[240:243], 0
	v_mfma_f32_16x16x32_bf16 v[18:21], v[170:173], v[240:243], 0
	v_mfma_f32_16x16x32_bf16 v[70:73], v[166:169], v[220:223], v[70:73]
	v_mfma_f32_16x16x32_bf16 v[66:69], v[174:177], v[220:223], v[66:69]
	v_mfma_f32_16x16x32_bf16 v[54:57], v[166:169], v[228:231], v[54:57]
	v_mfma_f32_16x16x32_bf16 v[50:53], v[174:177], v[228:231], v[50:53]
	v_mfma_f32_16x16x32_bf16 v[38:41], v[166:169], v[236:239], v[38:41]
	v_mfma_f32_16x16x32_bf16 v[34:37], v[174:177], v[236:239], v[34:37]
	v_mfma_f32_16x16x32_bf16 v[22:25], v[166:169], v[244:247], v[22:25]
	v_mfma_f32_16x16x32_bf16 v[18:21], v[174:177], v[244:247], v[18:21]
	s_setprio 0
	s_barrier
	v_add_u32_e32 v158, s82, v200
	v_add_u32_e32 v174, s83, v200
	ds_read_b128 v[146:149], v158
	ds_read_b128 v[150:153], v158 offset:1024
	ds_read_b128 v[154:157], v158 offset:2048
	ds_read_b128 v[158:161], v158 offset:3072
	ds_read_b128 v[162:165], v174
	ds_read_b128 v[166:169], v174 offset:1024
	ds_read_b128 v[170:173], v174 offset:2048
	ds_read_b128 v[174:177], v174 offset:3072
	s_add_u32 s28, s28, 0x40000
	s_addc_u32 s29, s29, 0
	s_mov_b32 m0, s61
	v_lshl_add_u64 v[208:209], s[28:29], 0, v[178:179]
	ds_read_b128 v[216:219], v202 offset:32768
	ds_read_b128 v[220:223], v202 offset:33792
	ds_read_b128 v[224:227], v202 offset:34816
	ds_read_b128 v[228:231], v202 offset:35840
	ds_read_b128 v[232:235], v202 offset:36864
	ds_read_b128 v[236:239], v202 offset:37888
	ds_read_b128 v[240:243], v202 offset:38912
	ds_read_b128 v[244:247], v202 offset:39936
	global_load_lds_dwordx4 v[208:209], off
	v_lshl_add_u64 v[208:209], s[28:29], 0, v[182:183]
	s_mov_b32 m0, s62
	s_nop 0
	global_load_lds_dwordx4 v[208:209], off
	s_waitcnt vmcnt(8)
	s_waitcnt lgkmcnt(0)
	s_barrier
	s_setprio 1
	s_waitcnt lgkmcnt(0)
	v_mfma_f32_16x16x32_bf16 v[142:145], v[146:149], v[216:219], v[142:145]
	v_mfma_f32_16x16x32_bf16 v[138:141], v[154:157], v[216:219], v[138:141]
	v_mfma_f32_16x16x32_bf16 v[126:129], v[146:149], v[224:227], v[126:129]
	v_mfma_f32_16x16x32_bf16 v[122:125], v[154:157], v[224:227], v[122:125]
	v_mfma_f32_16x16x32_bf16 v[110:113], v[146:149], v[232:235], v[110:113]
	v_mfma_f32_16x16x32_bf16 v[106:109], v[154:157], v[232:235], v[106:109]
	v_mfma_f32_16x16x32_bf16 v[94:97], v[146:149], v[240:243], v[94:97]
	v_mfma_f32_16x16x32_bf16 v[90:93], v[154:157], v[240:243], v[90:93]
	v_mfma_f32_16x16x32_bf16 v[142:145], v[150:153], v[220:223], v[142:145]
	v_mfma_f32_16x16x32_bf16 v[138:141], v[158:161], v[220:223], v[138:141]
	v_mfma_f32_16x16x32_bf16 v[126:129], v[150:153], v[228:231], v[126:129]
	v_mfma_f32_16x16x32_bf16 v[122:125], v[158:161], v[228:231], v[122:125]
	v_mfma_f32_16x16x32_bf16 v[110:113], v[150:153], v[236:239], v[110:113]
	v_mfma_f32_16x16x32_bf16 v[106:109], v[158:161], v[236:239], v[106:109]
	v_mfma_f32_16x16x32_bf16 v[94:97], v[150:153], v[244:247], v[94:97]
	v_mfma_f32_16x16x32_bf16 v[90:93], v[158:161], v[244:247], v[90:93]
	s_setprio 0
	s_setprio 1
	v_mfma_f32_16x16x32_bf16 v[134:137], v[162:165], v[216:219], v[134:137]
	v_mfma_f32_16x16x32_bf16 v[130:133], v[170:173], v[216:219], v[130:133]
	v_mfma_f32_16x16x32_bf16 v[118:121], v[162:165], v[224:227], v[118:121]
	v_mfma_f32_16x16x32_bf16 v[114:117], v[170:173], v[224:227], v[114:117]
	v_mfma_f32_16x16x32_bf16 v[102:105], v[162:165], v[232:235], v[102:105]
	v_mfma_f32_16x16x32_bf16 v[98:101], v[170:173], v[232:235], v[98:101]
	v_mfma_f32_16x16x32_bf16 v[86:89], v[162:165], v[240:243], v[86:89]
	v_mfma_f32_16x16x32_bf16 v[82:85], v[170:173], v[240:243], v[82:85]
	v_mfma_f32_16x16x32_bf16 v[134:137], v[166:169], v[220:223], v[134:137]
	v_mfma_f32_16x16x32_bf16 v[130:133], v[174:177], v[220:223], v[130:133]
	v_mfma_f32_16x16x32_bf16 v[118:121], v[166:169], v[228:231], v[118:121]
	v_mfma_f32_16x16x32_bf16 v[114:117], v[174:177], v[228:231], v[114:117]
	v_mfma_f32_16x16x32_bf16 v[102:105], v[166:169], v[236:239], v[102:105]
	v_mfma_f32_16x16x32_bf16 v[98:101], v[174:177], v[236:239], v[98:101]
	v_mfma_f32_16x16x32_bf16 v[86:89], v[166:169], v[244:247], v[86:89]
	v_mfma_f32_16x16x32_bf16 v[82:85], v[174:177], v[244:247], v[82:85]
	s_setprio 0
	s_barrier
; #define PG8_STAGE(bufoff, gbase, voff) do { _Pragma("unroll") for (int _i = 0; _i < 2; ++_i) \
;         __builtin_amdgcn_global_load_lds((const unsigned*)((const char*)(gbase) + (voff)[_i]), (PG8_LAS unsigned*)(lds + (bufoff) + ldsw + _i * 8192), 16, 0, 0); } while (0)
; #define PG8_LDA(dst, b, h) do { _Pragma("unroll") for (int m = 0; m < 4; ++m) _Pragma("unroll") for (int k = 0; k < 2; ++k) dst[m][k] = *(const PG8_LAS bf16x8*)(lds + PG8_SA(b, h) + aoff + m * 2048 + k * 1024); } while (0)
; #define PG8_MMA(ai, bj, At, Bt) do { __builtin_amdgcn_s_setprio(1); _Pragma("unroll") for (int m = 0; m < 4; ++m) _Pragma("unroll") for (int n = 0; n < 2; ++n) _Pragma("unroll") for (int k = 0; k < 2; ++k) \
;         acc[ai][bj][m][n] = __builtin_amdgcn_mfma_f32_16x16x32_bf16(Bt[n][k], At[m][k], acc[ai][bj][m][n], 0, 0, 0); __builtin_amdgcn_s_setprio(0); } while (0)
; #define PG8_WAIT_V(n) asm volatile("s_waitcnt vmcnt(" #n ")" ::: "memory")
; #define PG8_WAIT_L(n) asm volatile("s_waitcnt lgkmcnt(" #n ")" ::: "memory")
; #define PG8_BAR __builtin_amdgcn_s_barrier()
; #define PG8_SCHED __builtin_amdgcn_sched_barrier(0)
; template <class Epi, class Sched, bool ALIGN_EPI = false, bool SP2 = false>
; __device__ __forceinline__ void gemm_phase(PG8_LAS unsigned char* lds, const Gemm g, const Sched& S, const Epi& E) {
;     ...
;             PG8_LDA(At, 1, 1); PG8_STAGE(PG8_SB(1, 0), b3, voffB); PG8_STAGE(PG8_SB(1, 1), b3 + hstep, voffB); PG8_STAGE(PG8_SA(1, 0), a3, voffA);
;             PG8_WAIT_V(8); PG8_WAIT_L(0); PG8_BAR; PG8_MMA(1, 0, At, B0); PG8_MMA(1, 1, At, B1); PG8_BAR; PG8_SCHED;
	s_add_i32 s28, s82, s38
	v_lshl_add_u64 v[198:199], v[198:199], 0, s[46:47]
	s_mov_b32 m0, s28
	ds_read_b128 v[216:219], v202 offset:49152
	ds_read_b128 v[220:223], v202 offset:50176
	ds_read_b128 v[224:227], v202 offset:51200
	ds_read_b128 v[228:231], v202 offset:52224
	ds_read_b128 v[232:235], v202 offset:53248
	ds_read_b128 v[236:239], v202 offset:54272
	ds_read_b128 v[240:243], v202 offset:55296
	ds_read_b128 v[244:247], v202 offset:56320
	global_load_lds_dwordx4 v[198:199], off
	s_add_i32 m0, s28, 0x2000
	s_add_u32 s26, s26, 0x40080
	v_lshl_add_u64 v[198:199], v[248:249], 0, s[46:47]
	s_addc_u32 s27, s27, 0
	s_add_i32 s28, s83, s38
	global_load_lds_dwordx4 v[198:199], off
	v_lshl_add_u64 v[198:199], s[26:27], 0, v[180:181]
	s_mov_b32 m0, s28
	s_nop 0
	global_load_lds_dwordx4 v[198:199], off
	v_lshl_add_u64 v[198:199], s[26:27], 0, v[184:185]
	s_add_i32 m0, s28, 0x2000
	s_nop 0
	global_load_lds_dwordx4 v[198:199], off
	v_lshl_add_u64 v[198:199], v[250:251], 0, s[46:47]
	s_mov_b32 m0, s63
	s_nop 0
	global_load_lds_dwordx4 v[198:199], off
	v_lshl_add_u64 v[198:199], v[252:253], 0, s[46:47]
	s_mov_b32 m0, s64
	s_nop 0
	global_load_lds_dwordx4 v[198:199], off
	s_waitcnt vmcnt(8)
	s_waitcnt lgkmcnt(0)
	s_barrier
	s_setprio 1
	s_waitcnt lgkmcnt(0)
	v_mfma_f32_16x16x32_bf16 v[78:81], v[146:149], v[216:219], v[78:81]
	v_mfma_f32_16x16x32_bf16 v[74:77], v[154:157], v[216:219], v[74:77]
	v_mfma_f32_16x16x32_bf16 v[62:65], v[146:149], v[224:227], v[62:65]
	v_mfma_f32_16x16x32_bf16 v[58:61], v[154:157], v[224:227], v[58:61]
	v_mfma_f32_16x16x32_bf16 v[46:49], v[146:149], v[232:235], v[46:49]
	v_mfma_f32_16x16x32_bf16 v[42:45], v[154:157], v[232:235], v[42:45]
	v_mfma_f32_16x16x32_bf16 v[30:33], v[146:149], v[240:243], v[30:33]
	v_mfma_f32_16x16x32_bf16 v[26:29], v[154:157], v[240:243], v[26:29]
	v_mfma_f32_16x16x32_bf16 v[78:81], v[150:153], v[220:223], v[78:81]
	v_mfma_f32_16x16x32_bf16 v[74:77], v[158:161], v[220:223], v[74:77]
	v_mfma_f32_16x16x32_bf16 v[62:65], v[150:153], v[228:231], v[62:65]
	v_mfma_f32_16x16x32_bf16 v[58:61], v[158:161], v[228:231], v[58:61]
	v_mfma_f32_16x16x32_bf16 v[46:49], v[150:153], v[236:239], v[46:49]
	v_mfma_f32_16x16x32_bf16 v[42:45], v[158:161], v[236:239], v[42:45]
	v_mfma_f32_16x16x32_bf16 v[30:33], v[150:153], v[244:247], v[30:33]
	v_mfma_f32_16x16x32_bf16 v[26:29], v[158:161], v[244:247], v[26:29]
	s_setprio 0
	s_setprio 1
	v_mfma_f32_16x16x32_bf16 v[70:73], v[162:165], v[216:219], v[70:73]
	v_mfma_f32_16x16x32_bf16 v[66:69], v[170:173], v[216:219], v[66:69]
	v_mfma_f32_16x16x32_bf16 v[54:57], v[162:165], v[224:227], v[54:57]
	v_mfma_f32_16x16x32_bf16 v[50:53], v[170:173], v[224:227], v[50:53]
	v_mfma_f32_16x16x32_bf16 v[38:41], v[162:165], v[232:235], v[38:41]
	v_mfma_f32_16x16x32_bf16 v[34:37], v[170:173], v[232:235], v[34:37]
	v_mfma_f32_16x16x32_bf16 v[22:25], v[162:165], v[240:243], v[22:25]
	v_mfma_f32_16x16x32_bf16 v[18:21], v[170:173], v[240:243], v[18:21]
	v_mfma_f32_16x16x32_bf16 v[70:73], v[166:169], v[220:223], v[70:73]
	v_mfma_f32_16x16x32_bf16 v[66:69], v[174:177], v[220:223], v[66:69]
	v_mfma_f32_16x16x32_bf16 v[54:57], v[166:169], v[228:231], v[54:57]
	v_mfma_f32_16x16x32_bf16 v[50:53], v[174:177], v[228:231], v[50:53]
	v_mfma_f32_16x16x32_bf16 v[38:41], v[166:169], v[236:239], v[38:41]
	v_mfma_f32_16x16x32_bf16 v[34:37], v[174:177], v[236:239], v[34:37]
	v_mfma_f32_16x16x32_bf16 v[22:25], v[166:169], v[244:247], v[22:25]
	v_mfma_f32_16x16x32_bf16 v[18:21], v[174:177], v[244:247], v[18:21]
	s_setprio 0
	s_barrier
	s_add_i32 s52, s52, 2
	s_add_u32 s24, s24, 0x100
	s_addc_u32 s25, s25, 0
	s_add_u32 s44, s44, 0x100
	s_addc_u32 s45, s45, 0

; #define LAS __attribute__((address_space(3)))
; __device__ __forceinline__ unsigned pk2(float lo, float hi) { return f2bf(lo) | (f2bf(hi) << 16); }
; __device__ __forceinline__ float bflo(unsigned u) { return __uint_as_float(u << 16); }
; __device__ __forceinline__ float bfhi(unsigned u) { return __uint_as_float(u & 0xffff0000u); }
; __device__ __forceinline__ void rglru_unit(LAS unsigned char* lds, int unit, const bf16* PBp, bf16* MGp, float* SSQRp, const float* cw, const float* cbias, const float* wa, const float* ba, const float* wx, const float* bxp, const float* lam) {
;     ...
;             unsigned pkx[8];
; #pragma unroll
;             for (int q4 = 0; q4 < 4; ++q4) {
;                 f32x4 o = *(const LAS f32x4*)(CW + 4 * 64 + ch0 + q4 * 4);
; #pragma unroll
;                 for (int k = 0; k < 4; ++k) { const f32x4 wv = *(const LAS f32x4*)(CW + k * 64 + ch0 + q4 * 4);
; #pragma unroll
;                     for (int e = 0; e < 4; ++e) { const int ch = q4 * 4 + e; const unsigned w = ((ch >> 3) ? xv[k][1] : xv[k][0])[(ch & 7) >> 1]; const float x = (ch & 1) ? bfhi(w) : bflo(w); o[e] = fmaf(wv[e], x, o[e]); } }
;                 pkx[2 * q4] = pk2(o[0], o[1]); pkx[2 * q4 + 1] = pk2(o[2], o[3]);
;                 if ((ch0 >> 5) == hf) *(LAS f32x4*)(XRF + ctt * 32 + (ch0 & 31) + q4 * 4) = o;
;             }
;             *(LAS v4u*)(XRB + ctt * 72 + ch0) = (v4u){pkx[0], pkx[1], pkx[2], pkx[3]};
;             *(LAS v4u*)(XRB + ctt * 72 + ch0 + 8) = (v4u){pkx[4], pkx[5], pkx[6], pkx[7]};
;             *(LAS v4u*)(GBL + ctt * 32 + (tid & 3) * 8) = gv;
;         }
.LBB0_434:
	ds_read_b128 v[72:75], v129
	ds_read_b128 v[76:79], v130
	ds_read_b128 v[80:83], v130 offset:256
	ds_read_b128 v[84:87], v130 offset:512
	ds_read_b128 v[88:91], v130 offset:768
	ds_read_b128 v[92:95], v129 offset:16
	ds_read_b128 v[96:99], v130 offset:16
	ds_read_b128 v[108:111], v130 offset:272
	ds_read_b128 v[112:115], v130 offset:528
	ds_read_b128 v[116:119], v130 offset:784
	s_waitcnt vmcnt(9)
	s_waitcnt lgkmcnt(5)
	v_lshlrev_b32_e32 v2, 16, v4
	v_and_b32_e32 v3, 0xffff0000, v4
	v_lshlrev_b32_e32 v120, 16, v5
	v_and_b32_e32 v121, 0xffff0000, v5
	v_pk_fma_f32 v[72:73], v[76:77], v[2:3], v[72:73]
	v_pk_fma_f32 v[74:75], v[78:79], v[120:121], v[74:75]
	v_lshlrev_b32_e32 v2, 16, v12
	v_and_b32_e32 v3, 0xffff0000, v12
	v_lshlrev_b32_e32 v120, 16, v13
	v_and_b32_e32 v121, 0xffff0000, v13
	v_pk_fma_f32 v[72:73], v[80:81], v[2:3], v[72:73]
	v_pk_fma_f32 v[74:75], v[82:83], v[120:121], v[74:75]
	v_lshlrev_b32_e32 v2, 16, v24
	v_and_b32_e32 v3, 0xffff0000, v24
	v_lshlrev_b32_e32 v120, 16, v25
	v_and_b32_e32 v121, 0xffff0000, v25
	v_pk_fma_f32 v[72:73], v[84:85], v[2:3], v[72:73]
	v_pk_fma_f32 v[74:75], v[86:87], v[120:121], v[74:75]
	v_lshlrev_b32_e32 v2, 16, v40
	v_and_b32_e32 v3, 0xffff0000, v40
	v_lshlrev_b32_e32 v120, 16, v41
	v_and_b32_e32 v121, 0xffff0000, v41
	v_pk_fma_f32 v[72:73], v[88:89], v[2:3], v[72:73]
	v_pk_fma_f32 v[74:75], v[90:91], v[120:121], v[74:75]
	s_and_saveexec_b64 s[2:3], vcc
	ds_write_b128 v131, v[72:75] offset:18432
	s_or_b64 exec, exec, s[2:3]
	v_cvt_pk_bf16_f32 v4, v72, v73
	v_cvt_pk_bf16_f32 v5, v74, v75
	ds_read_b128 v[72:75], v129 offset:32
	ds_read_b128 v[76:79], v130 offset:32
	ds_read_b128 v[80:83], v130 offset:288
	ds_read_b128 v[84:87], v130 offset:544
	ds_read_b128 v[88:91], v130 offset:800
	s_waitcnt lgkmcnt(6)
	v_lshlrev_b32_e32 v2, 16, v6
	v_and_b32_e32 v3, 0xffff0000, v6
	v_lshlrev_b32_e32 v120, 16, v7
	v_and_b32_e32 v121, 0xffff0000, v7
	v_pk_fma_f32 v[92:93], v[96:97], v[2:3], v[92:93]
	v_pk_fma_f32 v[94:95], v[98:99], v[120:121], v[94:95]
	v_lshlrev_b32_e32 v2, 16, v14
	v_and_b32_e32 v3, 0xffff0000, v14
	v_lshlrev_b32_e32 v120, 16, v15
	v_and_b32_e32 v121, 0xffff0000, v15
	v_pk_fma_f32 v[92:93], v[108:109], v[2:3], v[92:93]
	v_pk_fma_f32 v[94:95], v[110:111], v[120:121], v[94:95]
	v_lshlrev_b32_e32 v2, 16, v26
	v_and_b32_e32 v3, 0xffff0000, v26
	v_lshlrev_b32_e32 v120, 16, v27
	v_and_b32_e32 v121, 0xffff0000, v27
	v_pk_fma_f32 v[92:93], v[112:113], v[2:3], v[92:93]
	v_pk_fma_f32 v[94:95], v[114:115], v[120:121], v[94:95]
	v_lshlrev_b32_e32 v2, 16, v42
	v_and_b32_e32 v3, 0xffff0000, v42
	v_lshlrev_b32_e32 v120, 16, v43
	v_and_b32_e32 v121, 0xffff0000, v43
	v_pk_fma_f32 v[92:93], v[116:117], v[2:3], v[92:93]
	v_pk_fma_f32 v[94:95], v[118:119], v[120:121], v[94:95]
	s_and_saveexec_b64 s[2:3], vcc
	ds_write_b128 v131, v[92:95] offset:18448
	s_or_b64 exec, exec, s[2:3]
	v_cvt_pk_bf16_f32 v6, v92, v93
	v_cvt_pk_bf16_f32 v7, v94, v95
	ds_read_b128 v[92:95], v129 offset:48
	ds_read_b128 v[96:99], v130 offset:48
	ds_read_b128 v[108:111], v130 offset:304
	ds_read_b128 v[112:115], v130 offset:560
	ds_read_b128 v[116:119], v130 offset:816
	s_waitcnt lgkmcnt(6)
	v_lshlrev_b32_e32 v2, 16, v8
	v_and_b32_e32 v3, 0xffff0000, v8
	v_lshlrev_b32_e32 v120, 16, v9
	v_and_b32_e32 v121, 0xffff0000, v9
	v_pk_fma_f32 v[72:73], v[76:77], v[2:3], v[72:73]
	v_pk_fma_f32 v[74:75], v[78:79], v[120:121], v[74:75]
	v_lshlrev_b32_e32 v2, 16, v16
	v_and_b32_e32 v3, 0xffff0000, v16
	v_lshlrev_b32_e32 v120, 16, v17
	v_and_b32_e32 v121, 0xffff0000, v17
	v_pk_fma_f32 v[72:73], v[80:81], v[2:3], v[72:73]
	v_pk_fma_f32 v[74:75], v[82:83], v[120:121], v[74:75]
	v_lshlrev_b32_e32 v2, 16, v28
	v_and_b32_e32 v3, 0xffff0000, v28
	v_lshlrev_b32_e32 v120, 16, v29
	v_and_b32_e32 v121, 0xffff0000, v29
	v_pk_fma_f32 v[72:73], v[84:85], v[2:3], v[72:73]
	v_pk_fma_f32 v[74:75], v[86:87], v[120:121], v[74:75]
	v_lshlrev_b32_e32 v2, 16, v44
	v_and_b32_e32 v3, 0xffff0000, v44
	v_lshlrev_b32_e32 v120, 16, v45
	v_and_b32_e32 v121, 0xffff0000, v45
	v_pk_fma_f32 v[72:73], v[88:89], v[2:3], v[72:73]
	v_pk_fma_f32 v[74:75], v[90:91], v[120:121], v[74:75]
	s_and_saveexec_b64 s[2:3], vcc
	ds_write_b128 v131, v[72:75] offset:18464
	s_or_b64 exec, exec, s[2:3]
	v_cvt_pk_bf16_f32 v8, v72, v73
	v_cvt_pk_bf16_f32 v9, v74, v75
	s_waitcnt lgkmcnt(1)
	v_lshlrev_b32_e32 v2, 16, v10
	v_and_b32_e32 v3, 0xffff0000, v10
	v_lshlrev_b32_e32 v120, 16, v11
	v_and_b32_e32 v121, 0xffff0000, v11
	v_pk_fma_f32 v[92:93], v[96:97], v[2:3], v[92:93]
	v_pk_fma_f32 v[94:95], v[98:99], v[120:121], v[94:95]
	v_lshlrev_b32_e32 v2, 16, v18
	v_and_b32_e32 v3, 0xffff0000, v18
	v_lshlrev_b32_e32 v120, 16, v19
	v_and_b32_e32 v121, 0xffff0000, v19
	v_pk_fma_f32 v[92:93], v[108:109], v[2:3], v[92:93]
	v_pk_fma_f32 v[94:95], v[110:111], v[120:121], v[94:95]
	v_lshlrev_b32_e32 v2, 16, v30
	v_and_b32_e32 v3, 0xffff0000, v30
	v_lshlrev_b32_e32 v120, 16, v31
	v_and_b32_e32 v121, 0xffff0000, v31
	v_pk_fma_f32 v[92:93], v[112:113], v[2:3], v[92:93]
	v_pk_fma_f32 v[94:95], v[114:115], v[120:121], v[94:95]
	v_lshlrev_b32_e32 v2, 16, v46
	v_and_b32_e32 v3, 0xffff0000, v46
	v_lshlrev_b32_e32 v120, 16, v47
	v_and_b32_e32 v121, 0xffff0000, v47
	v_pk_fma_f32 v[92:93], v[116:117], v[2:3], v[92:93]
	v_pk_fma_f32 v[94:95], v[118:119], v[120:121], v[94:95]
	s_and_saveexec_b64 s[2:3], vcc
	ds_write_b128 v131, v[92:95] offset:18480
	s_or_b64 exec, exec, s[2:3]
	v_cvt_pk_bf16_f32 v10, v92, v93
	v_cvt_pk_bf16_f32 v11, v94, v95
	s_cmpk_lg_i32 s44, 0x780
	ds_write_b128 v132, v[4:7]
	ds_write_b128 v132, v[8:11] offset:16
	s_waitcnt vmcnt(8)
	ds_write_b128 v133, v[68:71]
	s_cbranch_scc0 .LBB0_452
	v_add_u32_e32 v1, s44, v126
	v_mov_b32_e32 v12, v0
	v_mov_b32_e32 v13, v0
	v_add_u32_e32 v40, 0x7d, v1
	v_mov_b32_e32 v14, v0
	v_mov_b32_e32 v15, v0
	v_mov_b64_e32 v[4:5], v[12:13]
	v_mov_b64_e32 v[8:9], v[12:13]
	v_cmp_lt_i32_e64 s[2:3], -1, v40
	v_add_u32_e32 v68, s44, v142
	v_mov_b64_e32 v[6:7], v[14:15]
	v_mov_b64_e32 v[10:11], v[14:15]
	s_and_saveexec_b64 s[62:63], s[2:3]
	s_cbranch_execz .LBB0_445
	v_add_u32_e32 v1, 0x7d, v68
	v_mad_u64_u32 v[2:3], s[2:3], v1, s71, v[100:101]
	global_load_dwordx4 v[8:11], v[2:3], off offset:16
	global_load_dwordx4 v[4:7], v[2:3], off

; #define PG8_STAGE(bufoff, gbase, voff) do { _Pragma("unroll") for (int _i = 0; _i < 2; ++_i) \
;         __builtin_amdgcn_global_load_lds((const unsigned*)((const char*)(gbase) + (voff)[_i]), (PG8_LAS unsigned*)(lds + (bufoff) + ldsw + _i * 8192), 16, 0, 0); } while (0)
; #define PG8_LDA(dst, b, h) do { _Pragma("unroll") for (int m = 0; m < 4; ++m) _Pragma("unroll") for (int k = 0; k < 2; ++k) dst[m][k] = *(const PG8_LAS bf16x8*)(lds + PG8_SA(b, h) + aoff + m * 2048 + k * 1024); } while (0)
; #define PG8_LDB(dst, b, h) do { _Pragma("unroll") for (int n = 0; n < 2; ++n) _Pragma("unroll") for (int k = 0; k < 2; ++k) dst[n][k] = *(const PG8_LAS bf16x8*)(lds + PG8_SB(b, h) + boff + n * 2048 + k * 1024); } while (0)
; #define PG8_MMA(ai, bj, At, Bt) do { __builtin_amdgcn_s_setprio(1); _Pragma("unroll") for (int m = 0; m < 4; ++m) _Pragma("unroll") for (int n = 0; n < 2; ++n) _Pragma("unroll") for (int k = 0; k < 2; ++k) \
;         acc[ai][bj][m][n] = __builtin_amdgcn_mfma_f32_16x16x32_bf16(Bt[n][k], At[m][k], acc[ai][bj][m][n], 0, 0, 0); __builtin_amdgcn_s_setprio(0); } while (0)
; #define PG8_WAIT_V(n) asm volatile("s_waitcnt vmcnt(" #n ")" ::: "memory")
; #define PG8_WAIT_L(n) asm volatile("s_waitcnt lgkmcnt(" #n ")" ::: "memory")
; #define PG8_BAR __builtin_amdgcn_s_barrier()
; #define PG8_SCHED __builtin_amdgcn_sched_barrier(0)
; template <class Epi, class Sched, bool ALIGN_EPI = false, bool SP2 = false>
; __device__ __forceinline__ void gemm_phase(PG8_LAS unsigned char* lds, const Gemm g, const Sched& S, const Epi& E) {
;     ...
;             const char* a2 = last ? nA : cA + (size_t)(t + 2) * kstep; const char* b2 = last ? nB : cB + (size_t)(t + 2) * kstep;
;             const char* a3 = a2 + kstep; const char* b3 = b2 + kstep;
;             if (last && has_next) S.a_ready_inloop(nxt, ui + 1);
;             if constexpr (SP2) {
;             PG8_LDB(B0, 0, 0); PG8_LDB(B1, 0, 1); PG8_SCHED; PG8_LDA(At, 0, 0); PG8_STAGE(PG8_SA(1, 1), a1 + hstep, voffA);
;             PG8_WAIT_V(8); PG8_WAIT_L(0); PG8_BAR; PG8_MMA(0, 0, At, B0); PG8_MMA(0, 1, At, B1); PG8_BAR; PG8_SCHED;
;             PG8_LDA(At, 0, 1); PG8_STAGE(PG8_SB(0, 0), b2, voffB); PG8_STAGE(PG8_SB(0, 1), b2 + hstep, voffB); PG8_STAGE(PG8_SA(0, 0), a2, voffA);
;             PG8_WAIT_V(8); PG8_WAIT_L(0); PG8_BAR; PG8_MMA(1, 0, At, B0); PG8_MMA(1, 1, At, B1); PG8_BAR; PG8_SCHED;
.LBB0_761:
	s_ashr_i32 s13, s12, 31
	s_lshl_b64 s[16:17], s[12:13], 19
	s_add_u32 s16, s28, s16
	s_addc_u32 s17, s29, s17
	s_and_b64 s[18:19], s[2:3], exec
	s_cselect_b32 s13, s17, s21
	s_cselect_b32 s52, s16, s20
	s_ashr_i32 s15, s14, 31
	s_lshl_b64 s[18:19], s[14:15], 19
	s_add_u32 s18, s30, s18
	s_addc_u32 s19, s31, s19
	s_and_b64 s[24:25], s[2:3], exec
	s_cselect_b32 s15, s19, s23
	s_cselect_b32 s53, s18, s22
	s_add_u32 s20, s20, 0x40080
	s_addc_u32 s21, s21, 0
	s_add_u32 s62, s22, 0x100
	s_addc_u32 s63, s23, 0
	s_mov_b32 s64, -2
	v_add_u32_e32 v158, s90, v160
	ds_read_b128 v[164:167], v158
	ds_read_b128 v[168:171], v158 offset:1024
	ds_read_b128 v[172:175], v158 offset:2048
	ds_read_b128 v[176:179], v158 offset:3072
	v_add_u32_e32 v158, s81, v160
	ds_read_b128 v[180:183], v158
	ds_read_b128 v[184:187], v158 offset:1024
	ds_read_b128 v[188:191], v158 offset:2048
	ds_read_b128 v[192:195], v158 offset:3072
	s_add_u32 s22, s20, 0xfffc0080
	s_addc_u32 s23, s21, -1
	s_cmp_eq_u32 s64, 12
	s_cselect_b32 s25, s13, s23
	s_cselect_b32 s24, s52, s22
	s_cselect_b32 s23, s15, s63
	s_cselect_b32 s22, s53, s62
	v_lshl_add_u64 v[158:159], s[20:21], 0, v[154:155]
	s_add_i32 m0, s35, 0xc000
	ds_read_b128 v[196:199], v163
	ds_read_b128 v[200:203], v163 offset:1024
	ds_read_b128 v[216:219], v163 offset:2048
	ds_read_b128 v[220:223], v163 offset:3072
	ds_read_b128 v[224:227], v163 offset:4096
	ds_read_b128 v[228:231], v163 offset:5120
	ds_read_b128 v[232:235], v163 offset:6144
	ds_read_b128 v[236:239], v163 offset:7168
	global_load_lds_dwordx4 v[158:159], off
	v_lshl_add_u64 v[158:159], s[20:21], 0, v[156:157]
	s_add_i32 m0, s35, 0xe000
	s_nop 0
	global_load_lds_dwordx4 v[158:159], off
	s_waitcnt vmcnt(8)
	s_waitcnt lgkmcnt(0)
	s_barrier
	s_setprio 1
	s_waitcnt lgkmcnt(0)
	v_mfma_f32_16x16x32_bf16 v[142:145], v[164:167], v[196:199], 0
	v_mfma_f32_16x16x32_bf16 v[138:141], v[172:175], v[196:199], 0
	v_mfma_f32_16x16x32_bf16 v[126:129], v[164:167], v[216:219], 0
	v_mfma_f32_16x16x32_bf16 v[122:125], v[172:175], v[216:219], 0
	v_mfma_f32_16x16x32_bf16 v[110:113], v[164:167], v[224:227], 0
	v_mfma_f32_16x16x32_bf16 v[106:109], v[172:175], v[224:227], 0
	v_mfma_f32_16x16x32_bf16 v[94:97], v[164:167], v[232:235], 0
	v_mfma_f32_16x16x32_bf16 v[90:93], v[172:175], v[232:235], 0
	v_mfma_f32_16x16x32_bf16 v[142:145], v[168:171], v[200:203], v[142:145]
	v_mfma_f32_16x16x32_bf16 v[138:141], v[176:179], v[200:203], v[138:141]
	v_mfma_f32_16x16x32_bf16 v[126:129], v[168:171], v[220:223], v[126:129]
	v_mfma_f32_16x16x32_bf16 v[122:125], v[176:179], v[220:223], v[122:125]
	v_mfma_f32_16x16x32_bf16 v[110:113], v[168:171], v[228:231], v[110:113]
	v_mfma_f32_16x16x32_bf16 v[106:109], v[176:179], v[228:231], v[106:109]
	v_mfma_f32_16x16x32_bf16 v[94:97], v[168:171], v[236:239], v[94:97]
	v_mfma_f32_16x16x32_bf16 v[90:93], v[176:179], v[236:239], v[90:93]
	s_setprio 0
	s_setprio 1
	v_mfma_f32_16x16x32_bf16 v[134:137], v[180:183], v[196:199], 0
	v_mfma_f32_16x16x32_bf16 v[130:133], v[188:191], v[196:199], 0
	v_mfma_f32_16x16x32_bf16 v[118:121], v[180:183], v[216:219], 0
	v_mfma_f32_16x16x32_bf16 v[114:117], v[188:191], v[216:219], 0
	v_mfma_f32_16x16x32_bf16 v[102:105], v[180:183], v[224:227], 0
	v_mfma_f32_16x16x32_bf16 v[98:101], v[188:191], v[224:227], 0
	v_mfma_f32_16x16x32_bf16 v[86:89], v[180:183], v[232:235], 0
	v_mfma_f32_16x16x32_bf16 v[82:85], v[188:191], v[232:235], 0
	v_mfma_f32_16x16x32_bf16 v[134:137], v[184:187], v[200:203], v[134:137]
	v_mfma_f32_16x16x32_bf16 v[130:133], v[192:195], v[200:203], v[130:133]
	v_mfma_f32_16x16x32_bf16 v[118:121], v[184:187], v[220:223], v[118:121]
	v_mfma_f32_16x16x32_bf16 v[114:117], v[192:195], v[220:223], v[114:117]
	v_mfma_f32_16x16x32_bf16 v[102:105], v[184:187], v[228:231], v[102:105]
	v_mfma_f32_16x16x32_bf16 v[98:101], v[192:195], v[228:231], v[98:101]
	v_mfma_f32_16x16x32_bf16 v[86:89], v[184:187], v[236:239], v[86:89]
	v_mfma_f32_16x16x32_bf16 v[82:85], v[192:195], v[236:239], v[82:85]
	s_setprio 0
	s_barrier
	s_add_i32 s65, s90, s34
	v_lshl_add_u64 v[158:159], s[22:23], 0, v[148:149]
	s_mov_b32 m0, s65
	ds_read_b128 v[196:199], v163 offset:16384
	ds_read_b128 v[200:203], v163 offset:17408
	ds_read_b128 v[216:219], v163 offset:18432
	ds_read_b128 v[220:223], v163 offset:19456
	ds_read_b128 v[224:227], v163 offset:20480
	ds_read_b128 v[228:231], v163 offset:21504
	ds_read_b128 v[232:235], v163 offset:22528
	ds_read_b128 v[236:239], v163 offset:23552
	global_load_lds_dwordx4 v[158:159], off
	s_add_i32 m0, s65, 0x2000
	s_add_u32 s66, s22, 0x40000
	v_lshl_add_u64 v[208:209], s[22:23], 0, v[152:153]
	s_addc_u32 s67, s23, 0
	s_add_i32 s65, s81, s34
	global_load_lds_dwordx4 v[208:209], off
	v_lshl_add_u64 v[210:211], s[66:67], 0, v[148:149]
	s_mov_b32 m0, s65
	v_lshl_add_u64 v[240:241], s[24:25], 0, v[150:151]
	global_load_lds_dwordx4 v[210:211], off
	v_lshl_add_u64 v[210:211], s[66:67], 0, v[152:153]
	s_add_i32 m0, s65, 0x2000
	s_nop 0
	global_load_lds_dwordx4 v[210:211], off
	v_lshl_add_u64 v[210:211], s[24:25], 0, v[146:147]
	s_mov_b32 m0, s35
	s_nop 0
	global_load_lds_dwordx4 v[210:211], off
	s_mov_b32 m0, s36
	s_nop 0
	global_load_lds_dwordx4 v[240:241], off
	s_waitcnt vmcnt(8)
	s_waitcnt lgkmcnt(0)
	s_barrier
; #define PG8_STAGE(bufoff, gbase, voff) do { _Pragma("unroll") for (int _i = 0; _i < 2; ++_i) \
;         __builtin_amdgcn_global_load_lds((const unsigned*)((const char*)(gbase) + (voff)[_i]), (PG8_LAS unsigned*)(lds + (bufoff) + ldsw + _i * 8192), 16, 0, 0); } while (0)
; #define PG8_LDA(dst, b, h) do { _Pragma("unroll") for (int m = 0; m < 4; ++m) _Pragma("unroll") for (int k = 0; k < 2; ++k) dst[m][k] = *(const PG8_LAS bf16x8*)(lds + PG8_SA(b, h) + aoff + m * 2048 + k * 1024); } while (0)
; #define PG8_LDB(dst, b, h) do { _Pragma("unroll") for (int n = 0; n < 2; ++n) _Pragma("unroll") for (int k = 0; k < 2; ++k) dst[n][k] = *(const PG8_LAS bf16x8*)(lds + PG8_SB(b, h) + boff + n * 2048 + k * 1024); } while (0)
; #define PG8_MMA(ai, bj, At, Bt) do { __builtin_amdgcn_s_setprio(1); _Pragma("unroll") for (int m = 0; m < 4; ++m) _Pragma("unroll") for (int n = 0; n < 2; ++n) _Pragma("unroll") for (int k = 0; k < 2; ++k) \
;         acc[ai][bj][m][n] = __builtin_amdgcn_mfma_f32_16x16x32_bf16(Bt[n][k], At[m][k], acc[ai][bj][m][n], 0, 0, 0); __builtin_amdgcn_s_setprio(0); } while (0)
; #define PG8_WAIT_V(n) asm volatile("s_waitcnt vmcnt(" #n ")" ::: "memory")
; #define PG8_WAIT_L(n) asm volatile("s_waitcnt lgkmcnt(" #n ")" ::: "memory")
; #define PG8_BAR __builtin_amdgcn_s_barrier()
; #define PG8_SCHED __builtin_amdgcn_sched_barrier(0)
; template <class Epi, class Sched, bool ALIGN_EPI = false, bool SP2 = false>
; __device__ __forceinline__ void gemm_phase(PG8_LAS unsigned char* lds, const Gemm g, const Sched& S, const Epi& E) {
;     ...
;             PG8_WAIT_V(8); PG8_WAIT_L(0); PG8_BAR; PG8_MMA(1, 0, At, B0); PG8_MMA(1, 1, At, B1); PG8_BAR; PG8_SCHED;
;             PG8_LDB(B0, 1, 0); PG8_LDB(B1, 1, 1); PG8_SCHED; PG8_LDA(At, 1, 0); PG8_STAGE(PG8_SA(0, 1), a2 + hstep, voffA);
;             PG8_WAIT_V(8); PG8_WAIT_L(0); PG8_BAR; PG8_MMA(0, 0, At, B0); PG8_MMA(0, 1, At, B1); PG8_BAR; PG8_SCHED;
	s_setprio 1
	s_waitcnt lgkmcnt(0)
	v_mfma_f32_16x16x32_bf16 v[78:81], v[164:167], v[196:199], 0
	v_mfma_f32_16x16x32_bf16 v[74:77], v[172:175], v[196:199], 0
	v_mfma_f32_16x16x32_bf16 v[62:65], v[164:167], v[216:219], 0
	v_mfma_f32_16x16x32_bf16 v[58:61], v[172:175], v[216:219], 0
	v_mfma_f32_16x16x32_bf16 v[46:49], v[164:167], v[224:227], 0
	v_mfma_f32_16x16x32_bf16 v[42:45], v[172:175], v[224:227], 0
	v_mfma_f32_16x16x32_bf16 v[30:33], v[164:167], v[232:235], 0
	v_mfma_f32_16x16x32_bf16 v[26:29], v[172:175], v[232:235], 0
	v_mfma_f32_16x16x32_bf16 v[78:81], v[168:171], v[200:203], v[78:81]
	v_mfma_f32_16x16x32_bf16 v[74:77], v[176:179], v[200:203], v[74:77]
	v_mfma_f32_16x16x32_bf16 v[62:65], v[168:171], v[220:223], v[62:65]
	v_mfma_f32_16x16x32_bf16 v[58:61], v[176:179], v[220:223], v[58:61]
	v_mfma_f32_16x16x32_bf16 v[46:49], v[168:171], v[228:231], v[46:49]
	v_mfma_f32_16x16x32_bf16 v[42:45], v[176:179], v[228:231], v[42:45]
	v_mfma_f32_16x16x32_bf16 v[30:33], v[168:171], v[236:239], v[30:33]
	v_mfma_f32_16x16x32_bf16 v[26:29], v[176:179], v[236:239], v[26:29]
	s_setprio 0
	s_setprio 1
	v_mfma_f32_16x16x32_bf16 v[70:73], v[180:183], v[196:199], 0
	v_mfma_f32_16x16x32_bf16 v[66:69], v[188:191], v[196:199], 0
	v_mfma_f32_16x16x32_bf16 v[54:57], v[180:183], v[216:219], 0
	v_mfma_f32_16x16x32_bf16 v[50:53], v[188:191], v[216:219], 0
	v_mfma_f32_16x16x32_bf16 v[38:41], v[180:183], v[224:227], 0
	v_mfma_f32_16x16x32_bf16 v[34:37], v[188:191], v[224:227], 0
	v_mfma_f32_16x16x32_bf16 v[22:25], v[180:183], v[232:235], 0
	v_mfma_f32_16x16x32_bf16 v[18:21], v[188:191], v[232:235], 0
	v_mfma_f32_16x16x32_bf16 v[70:73], v[184:187], v[200:203], v[70:73]
	v_mfma_f32_16x16x32_bf16 v[66:69], v[192:195], v[200:203], v[66:69]
	v_mfma_f32_16x16x32_bf16 v[54:57], v[184:187], v[220:223], v[54:57]
	v_mfma_f32_16x16x32_bf16 v[50:53], v[192:195], v[220:223], v[50:53]
	v_mfma_f32_16x16x32_bf16 v[38:41], v[184:187], v[228:231], v[38:41]
	v_mfma_f32_16x16x32_bf16 v[34:37], v[192:195], v[228:231], v[34:37]
	v_mfma_f32_16x16x32_bf16 v[22:25], v[184:187], v[236:239], v[22:25]
	v_mfma_f32_16x16x32_bf16 v[18:21], v[192:195], v[236:239], v[18:21]
	s_setprio 0
	s_barrier
	v_add_u32_e32 v176, s82, v160
	v_add_u32_e32 v192, s83, v160
	ds_read_b128 v[164:167], v176
	ds_read_b128 v[168:171], v176 offset:1024
	ds_read_b128 v[172:175], v176 offset:2048
	ds_read_b128 v[176:179], v176 offset:3072
	ds_read_b128 v[180:183], v192
	ds_read_b128 v[184:187], v192 offset:1024
	ds_read_b128 v[188:191], v192 offset:2048
	ds_read_b128 v[192:195], v192 offset:3072
	s_add_u32 s24, s24, 0x40000
	s_addc_u32 s25, s25, 0
	s_mov_b32 m0, s37
	v_lshl_add_u64 v[242:243], s[24:25], 0, v[146:147]
	ds_read_b128 v[196:199], v163 offset:32768
	ds_read_b128 v[200:203], v163 offset:33792
	ds_read_b128 v[216:219], v163 offset:34816
	ds_read_b128 v[220:223], v163 offset:35840
	ds_read_b128 v[224:227], v163 offset:36864
	ds_read_b128 v[228:231], v163 offset:37888
	ds_read_b128 v[232:235], v163 offset:38912
	ds_read_b128 v[236:239], v163 offset:39936
	global_load_lds_dwordx4 v[242:243], off
	v_lshl_add_u64 v[242:243], s[24:25], 0, v[150:151]
	s_mov_b32 m0, s38
	s_nop 0
	global_load_lds_dwordx4 v[242:243], off
	s_waitcnt vmcnt(8)
	s_waitcnt lgkmcnt(0)
	s_barrier
	s_setprio 1
	s_waitcnt lgkmcnt(0)
	v_mfma_f32_16x16x32_bf16 v[142:145], v[164:167], v[196:199], v[142:145]
	v_mfma_f32_16x16x32_bf16 v[138:141], v[172:175], v[196:199], v[138:141]
	v_mfma_f32_16x16x32_bf16 v[126:129], v[164:167], v[216:219], v[126:129]
	v_mfma_f32_16x16x32_bf16 v[122:125], v[172:175], v[216:219], v[122:125]
	v_mfma_f32_16x16x32_bf16 v[110:113], v[164:167], v[224:227], v[110:113]
	v_mfma_f32_16x16x32_bf16 v[106:109], v[172:175], v[224:227], v[106:109]
	v_mfma_f32_16x16x32_bf16 v[94:97], v[164:167], v[232:235], v[94:97]
	v_mfma_f32_16x16x32_bf16 v[90:93], v[172:175], v[232:235], v[90:93]
	v_mfma_f32_16x16x32_bf16 v[142:145], v[168:171], v[200:203], v[142:145]
	v_mfma_f32_16x16x32_bf16 v[138:141], v[176:179], v[200:203], v[138:141]
	v_mfma_f32_16x16x32_bf16 v[126:129], v[168:171], v[220:223], v[126:129]
	v_mfma_f32_16x16x32_bf16 v[122:125], v[176:179], v[220:223], v[122:125]
	v_mfma_f32_16x16x32_bf16 v[110:113], v[168:171], v[228:231], v[110:113]
	v_mfma_f32_16x16x32_bf16 v[106:109], v[176:179], v[228:231], v[106:109]
	v_mfma_f32_16x16x32_bf16 v[94:97], v[168:171], v[236:239], v[94:97]
	v_mfma_f32_16x16x32_bf16 v[90:93], v[176:179], v[236:239], v[90:93]
	s_setprio 0
	s_setprio 1
	v_mfma_f32_16x16x32_bf16 v[134:137], v[180:183], v[196:199], v[134:137]
	v_mfma_f32_16x16x32_bf16 v[130:133], v[188:191], v[196:199], v[130:133]
	v_mfma_f32_16x16x32_bf16 v[118:121], v[180:183], v[216:219], v[118:121]
	v_mfma_f32_16x16x32_bf16 v[114:117], v[188:191], v[216:219], v[114:117]
	v_mfma_f32_16x16x32_bf16 v[102:105], v[180:183], v[224:227], v[102:105]
	v_mfma_f32_16x16x32_bf16 v[98:101], v[188:191], v[224:227], v[98:101]
	v_mfma_f32_16x16x32_bf16 v[86:89], v[180:183], v[232:235], v[86:89]
	v_mfma_f32_16x16x32_bf16 v[82:85], v[188:191], v[232:235], v[82:85]
	v_mfma_f32_16x16x32_bf16 v[134:137], v[184:187], v[200:203], v[134:137]
	v_mfma_f32_16x16x32_bf16 v[130:133], v[192:195], v[200:203], v[130:133]
	v_mfma_f32_16x16x32_bf16 v[118:121], v[184:187], v[220:223], v[118:121]
	v_mfma_f32_16x16x32_bf16 v[114:117], v[192:195], v[220:223], v[114:117]
	v_mfma_f32_16x16x32_bf16 v[102:105], v[184:187], v[228:231], v[102:105]
	v_mfma_f32_16x16x32_bf16 v[98:101], v[192:195], v[228:231], v[98:101]
	v_mfma_f32_16x16x32_bf16 v[86:89], v[184:187], v[236:239], v[86:89]
	v_mfma_f32_16x16x32_bf16 v[82:85], v[192:195], v[236:239], v[82:85]
	s_setprio 0
	s_barrier
; #define PG8_STAGE(bufoff, gbase, voff) do { _Pragma("unroll") for (int _i = 0; _i < 2; ++_i) \
;         __builtin_amdgcn_global_load_lds((const unsigned*)((const char*)(gbase) + (voff)[_i]), (PG8_LAS unsigned*)(lds + (bufoff) + ldsw + _i * 8192), 16, 0, 0); } while (0)
; #define PG8_LDA(dst, b, h) do { _Pragma("unroll") for (int m = 0; m < 4; ++m) _Pragma("unroll") for (int k = 0; k < 2; ++k) dst[m][k] = *(const PG8_LAS bf16x8*)(lds + PG8_SA(b, h) + aoff + m * 2048 + k * 1024); } while (0)
; #define PG8_MMA(ai, bj, At, Bt) do { __builtin_amdgcn_s_setprio(1); _Pragma("unroll") for (int m = 0; m < 4; ++m) _Pragma("unroll") for (int n = 0; n < 2; ++n) _Pragma("unroll") for (int k = 0; k < 2; ++k) \
;         acc[ai][bj][m][n] = __builtin_amdgcn_mfma_f32_16x16x32_bf16(Bt[n][k], At[m][k], acc[ai][bj][m][n], 0, 0, 0); __builtin_amdgcn_s_setprio(0); } while (0)
; #define PG8_WAIT_V(n) asm volatile("s_waitcnt vmcnt(" #n ")" ::: "memory")
; #define PG8_WAIT_L(n) asm volatile("s_waitcnt lgkmcnt(" #n ")" ::: "memory")
; #define PG8_BAR __builtin_amdgcn_s_barrier()
; #define PG8_SCHED __builtin_amdgcn_sched_barrier(0)
; template <class Epi, class Sched, bool ALIGN_EPI = false, bool SP2 = false>
; __device__ __forceinline__ void gemm_phase(PG8_LAS unsigned char* lds, const Gemm g, const Sched& S, const Epi& E) {
;     ...
;             PG8_LDA(At, 1, 1); PG8_STAGE(PG8_SB(1, 0), b3, voffB); PG8_STAGE(PG8_SB(1, 1), b3 + hstep, voffB); PG8_STAGE(PG8_SA(1, 0), a3, voffA);
;             PG8_WAIT_V(8); PG8_WAIT_L(0); PG8_BAR; PG8_MMA(1, 0, At, B0); PG8_MMA(1, 1, At, B1); PG8_BAR; PG8_SCHED;
	s_add_i32 s24, s82, s34
	v_lshl_add_u64 v[158:159], v[158:159], 0, s[46:47]
	s_mov_b32 m0, s24
	ds_read_b128 v[196:199], v163 offset:49152
	ds_read_b128 v[200:203], v163 offset:50176
	ds_read_b128 v[216:219], v163 offset:51200
	ds_read_b128 v[220:223], v163 offset:52224
	ds_read_b128 v[224:227], v163 offset:53248
	ds_read_b128 v[228:231], v163 offset:54272
	ds_read_b128 v[232:235], v163 offset:55296
	ds_read_b128 v[236:239], v163 offset:56320
	global_load_lds_dwordx4 v[158:159], off
	s_add_i32 m0, s24, 0x2000
	s_add_u32 s22, s22, 0x40080
	v_lshl_add_u64 v[158:159], v[208:209], 0, s[46:47]
	s_addc_u32 s23, s23, 0
	s_add_i32 s24, s83, s34
	global_load_lds_dwordx4 v[158:159], off
	v_lshl_add_u64 v[158:159], s[22:23], 0, v[148:149]
	s_mov_b32 m0, s24
	s_nop 0
	global_load_lds_dwordx4 v[158:159], off
	v_lshl_add_u64 v[158:159], s[22:23], 0, v[152:153]
	s_add_i32 m0, s24, 0x2000
	s_nop 0
	global_load_lds_dwordx4 v[158:159], off
	v_lshl_add_u64 v[158:159], v[210:211], 0, s[46:47]
	s_mov_b32 m0, s39
	s_nop 0
	global_load_lds_dwordx4 v[158:159], off
	v_lshl_add_u64 v[158:159], v[240:241], 0, s[46:47]
	s_mov_b32 m0, s42
	s_nop 0
	global_load_lds_dwordx4 v[158:159], off
	s_waitcnt vmcnt(8)
	s_waitcnt lgkmcnt(0)
	s_barrier
	s_setprio 1
	s_waitcnt lgkmcnt(0)
	v_mfma_f32_16x16x32_bf16 v[78:81], v[164:167], v[196:199], v[78:81]
	v_mfma_f32_16x16x32_bf16 v[74:77], v[172:175], v[196:199], v[74:77]
	v_mfma_f32_16x16x32_bf16 v[62:65], v[164:167], v[216:219], v[62:65]
	v_mfma_f32_16x16x32_bf16 v[58:61], v[172:175], v[216:219], v[58:61]
	v_mfma_f32_16x16x32_bf16 v[46:49], v[164:167], v[224:227], v[46:49]
	v_mfma_f32_16x16x32_bf16 v[42:45], v[172:175], v[224:227], v[42:45]
	v_mfma_f32_16x16x32_bf16 v[30:33], v[164:167], v[232:235], v[30:33]
	v_mfma_f32_16x16x32_bf16 v[26:29], v[172:175], v[232:235], v[26:29]
	v_mfma_f32_16x16x32_bf16 v[78:81], v[168:171], v[200:203], v[78:81]
	v_mfma_f32_16x16x32_bf16 v[74:77], v[176:179], v[200:203], v[74:77]
	v_mfma_f32_16x16x32_bf16 v[62:65], v[168:171], v[220:223], v[62:65]
	v_mfma_f32_16x16x32_bf16 v[58:61], v[176:179], v[220:223], v[58:61]
	v_mfma_f32_16x16x32_bf16 v[46:49], v[168:171], v[228:231], v[46:49]
	v_mfma_f32_16x16x32_bf16 v[42:45], v[176:179], v[228:231], v[42:45]
	v_mfma_f32_16x16x32_bf16 v[30:33], v[168:171], v[236:239], v[30:33]
	v_mfma_f32_16x16x32_bf16 v[26:29], v[176:179], v[236:239], v[26:29]
	s_setprio 0
	s_setprio 1
	v_mfma_f32_16x16x32_bf16 v[70:73], v[180:183], v[196:199], v[70:73]
	v_mfma_f32_16x16x32_bf16 v[66:69], v[188:191], v[196:199], v[66:69]
	v_mfma_f32_16x16x32_bf16 v[54:57], v[180:183], v[216:219], v[54:57]
	v_mfma_f32_16x16x32_bf16 v[50:53], v[188:191], v[216:219], v[50:53]
	v_mfma_f32_16x16x32_bf16 v[38:41], v[180:183], v[224:227], v[38:41]
	v_mfma_f32_16x16x32_bf16 v[34:37], v[188:191], v[224:227], v[34:37]
	v_mfma_f32_16x16x32_bf16 v[22:25], v[180:183], v[232:235], v[22:25]
	v_mfma_f32_16x16x32_bf16 v[18:21], v[188:191], v[232:235], v[18:21]
	v_mfma_f32_16x16x32_bf16 v[70:73], v[184:187], v[200:203], v[70:73]
	v_mfma_f32_16x16x32_bf16 v[66:69], v[192:195], v[200:203], v[66:69]
	v_mfma_f32_16x16x32_bf16 v[54:57], v[184:187], v[220:223], v[54:57]
	v_mfma_f32_16x16x32_bf16 v[50:53], v[192:195], v[220:223], v[50:53]
	v_mfma_f32_16x16x32_bf16 v[38:41], v[184:187], v[228:231], v[38:41]
	v_mfma_f32_16x16x32_bf16 v[34:37], v[192:195], v[228:231], v[34:37]
	v_mfma_f32_16x16x32_bf16 v[22:25], v[184:187], v[236:239], v[22:25]
	v_mfma_f32_16x16x32_bf16 v[18:21], v[192:195], v[236:239], v[18:21]
	s_setprio 0
	s_barrier
	s_add_i32 s64, s64, 2
	s_add_u32 s20, s20, 0x100
	s_addc_u32 s21, s21, 0
	s_add_u32 s62, s62, 0x100
	s_addc_u32 s63, s63, 0

; #define PG8_STAGE(bufoff, gbase, voff) do { _Pragma("unroll") for (int _i = 0; _i < 2; ++_i) \
;         __builtin_amdgcn_global_load_lds((const unsigned*)((const char*)(gbase) + (voff)[_i]), (PG8_LAS unsigned*)(lds + (bufoff) + ldsw + _i * 8192), 16, 0, 0); } while (0)
; #define PG8_LDA(dst, b, h) do { _Pragma("unroll") for (int m = 0; m < 4; ++m) _Pragma("unroll") for (int k = 0; k < 2; ++k) dst[m][k] = *(const PG8_LAS bf16x8*)(lds + PG8_SA(b, h) + aoff + m * 2048 + k * 1024); } while (0)
; #define PG8_LDB(dst, b, h) do { _Pragma("unroll") for (int n = 0; n < 2; ++n) _Pragma("unroll") for (int k = 0; k < 2; ++k) dst[n][k] = *(const PG8_LAS bf16x8*)(lds + PG8_SB(b, h) + boff + n * 2048 + k * 1024); } while (0)
; #define PG8_MMA(ai, bj, At, Bt) do { __builtin_amdgcn_s_setprio(1); _Pragma("unroll") for (int m = 0; m < 4; ++m) _Pragma("unroll") for (int n = 0; n < 2; ++n) _Pragma("unroll") for (int k = 0; k < 2; ++k) \
;         acc[ai][bj][m][n] = __builtin_amdgcn_mfma_f32_16x16x32_bf16(Bt[n][k], At[m][k], acc[ai][bj][m][n], 0, 0, 0); __builtin_amdgcn_s_setprio(0); } while (0)
; #define PG8_WAIT_V(n) asm volatile("s_waitcnt vmcnt(" #n ")" ::: "memory")
; #define PG8_WAIT_L(n) asm volatile("s_waitcnt lgkmcnt(" #n ")" ::: "memory")
; #define PG8_BAR __builtin_amdgcn_s_barrier()
; #define PG8_SCHED __builtin_amdgcn_sched_barrier(0)
; template <class Epi, class Sched, bool ALIGN_EPI = false, bool SP2 = false>
; __device__ __forceinline__ void gemm_phase(PG8_LAS unsigned char* lds, const Gemm g, const Sched& S, const Epi& E) {
;     ...
;             const char* a2 = last ? nA : cA + (size_t)(t + 2) * kstep; const char* b2 = last ? nB : cB + (size_t)(t + 2) * kstep;
;             const char* a3 = a2 + kstep; const char* b3 = b2 + kstep;
;             if (last && has_next) S.a_ready_inloop(nxt, ui + 1);
;             if constexpr (SP2) {
;             PG8_LDB(B0, 0, 0); PG8_LDB(B1, 0, 1); PG8_SCHED; PG8_LDA(At, 0, 0); PG8_STAGE(PG8_SA(1, 1), a1 + hstep, voffA);
;             PG8_WAIT_V(8); PG8_WAIT_L(0); PG8_BAR; PG8_MMA(0, 0, At, B0); PG8_MMA(0, 1, At, B1); PG8_BAR; PG8_SCHED;
;             PG8_LDA(At, 0, 1); PG8_STAGE(PG8_SB(0, 0), b2, voffB); PG8_STAGE(PG8_SB(0, 1), b2 + hstep, voffB); PG8_STAGE(PG8_SA(0, 0), a2, voffA);
;             PG8_WAIT_V(8); PG8_WAIT_L(0); PG8_BAR; PG8_MMA(1, 0, At, B0); PG8_MMA(1, 1, At, B1); PG8_BAR; PG8_SCHED;
.LBB0_852:
	s_mov_b64 s[18:19], s[6:7]
	s_mov_b64 s[20:21], s[14:15]
	s_and_b64 s[6:7], s[16:17], exec
	s_cselect_b32 s7, s37, s19
	s_cselect_b32 s6, s36, s18
	s_cselect_b32 s15, s3, s21
	s_cselect_b32 s14, s2, s20
	s_add_u32 s39, s20, 0x100
	s_addc_u32 s42, s21, 0
	s_mov_b32 s44, -2
	v_add_u32_e32 v142, s90, v188
	v_add_u32_e32 v172, s81, v188
	ds_read_b128 v[130:133], v142
	ds_read_b128 v[134:137], v142 offset:1024
	ds_read_b128 v[138:141], v142 offset:2048
	ds_read_b128 v[142:145], v142 offset:3072
	ds_read_b128 v[146:149], v172
	ds_read_b128 v[150:153], v172 offset:1024
	ds_read_b128 v[154:157], v172 offset:2048
	ds_read_b128 v[172:175], v172 offset:3072
	s_add_u32 s20, s18, 0x100
	s_addc_u32 s21, s19, 0
	s_cmp_eq_u32 s44, 40
	s_cselect_b32 s25, s7, s21
	s_cselect_b32 s24, s6, s20
	s_cselect_b32 s23, s15, s42
	s_cselect_b32 s22, s14, s39
	v_lshl_add_u64 v[202:203], s[18:19], 0, v[168:169]
	s_add_i32 m0, s27, 0xc000
	ds_read_b128 v[176:179], v189
	ds_read_b128 v[180:183], v189 offset:1024
	ds_read_b128 v[184:187], v189 offset:2048
	ds_read_b128 v[190:193], v189 offset:3072
	ds_read_b128 v[194:197], v189 offset:4096
	ds_read_b128 v[198:201], v189 offset:5120
	ds_read_b128 v[216:219], v189 offset:6144
	ds_read_b128 v[220:223], v189 offset:7168
	global_load_lds_dwordx4 v[202:203], off
	v_lshl_add_u64 v[202:203], s[18:19], 0, v[170:171]
	s_add_i32 m0, s27, 0xe000
	s_nop 0
	global_load_lds_dwordx4 v[202:203], off
	s_waitcnt vmcnt(8)
	s_waitcnt lgkmcnt(0)
	s_barrier
	s_setprio 1
	s_waitcnt lgkmcnt(0)
	v_mfma_f32_16x16x32_bf16 v[126:129], v[130:133], v[176:179], 0
	v_mfma_f32_16x16x32_bf16 v[122:125], v[138:141], v[176:179], 0
	v_mfma_f32_16x16x32_bf16 v[110:113], v[130:133], v[184:187], 0
	v_mfma_f32_16x16x32_bf16 v[106:109], v[138:141], v[184:187], 0
	v_mfma_f32_16x16x32_bf16 v[94:97], v[130:133], v[194:197], 0
	v_mfma_f32_16x16x32_bf16 v[90:93], v[138:141], v[194:197], 0
	v_mfma_f32_16x16x32_bf16 v[78:81], v[130:133], v[216:219], 0
	v_mfma_f32_16x16x32_bf16 v[74:77], v[138:141], v[216:219], 0
	v_mfma_f32_16x16x32_bf16 v[126:129], v[134:137], v[180:183], v[126:129]
	v_mfma_f32_16x16x32_bf16 v[122:125], v[142:145], v[180:183], v[122:125]
	v_mfma_f32_16x16x32_bf16 v[110:113], v[134:137], v[190:193], v[110:113]
	v_mfma_f32_16x16x32_bf16 v[106:109], v[142:145], v[190:193], v[106:109]
	v_mfma_f32_16x16x32_bf16 v[94:97], v[134:137], v[198:201], v[94:97]
	v_mfma_f32_16x16x32_bf16 v[90:93], v[142:145], v[198:201], v[90:93]
	v_mfma_f32_16x16x32_bf16 v[78:81], v[134:137], v[220:223], v[78:81]
	v_mfma_f32_16x16x32_bf16 v[74:77], v[142:145], v[220:223], v[74:77]
	s_setprio 0
	s_setprio 1
	v_mfma_f32_16x16x32_bf16 v[118:121], v[146:149], v[176:179], 0
	v_mfma_f32_16x16x32_bf16 v[114:117], v[154:157], v[176:179], 0
	v_mfma_f32_16x16x32_bf16 v[102:105], v[146:149], v[184:187], 0
	v_mfma_f32_16x16x32_bf16 v[98:101], v[154:157], v[184:187], 0
	v_mfma_f32_16x16x32_bf16 v[86:89], v[146:149], v[194:197], 0
	v_mfma_f32_16x16x32_bf16 v[82:85], v[154:157], v[194:197], 0
	v_mfma_f32_16x16x32_bf16 v[70:73], v[146:149], v[216:219], 0
	v_mfma_f32_16x16x32_bf16 v[66:69], v[154:157], v[216:219], 0
	v_mfma_f32_16x16x32_bf16 v[118:121], v[150:153], v[180:183], v[118:121]
	v_mfma_f32_16x16x32_bf16 v[114:117], v[172:175], v[180:183], v[114:117]
	v_mfma_f32_16x16x32_bf16 v[102:105], v[150:153], v[190:193], v[102:105]
	v_mfma_f32_16x16x32_bf16 v[98:101], v[172:175], v[190:193], v[98:101]
	v_mfma_f32_16x16x32_bf16 v[86:89], v[150:153], v[198:201], v[86:89]
	v_mfma_f32_16x16x32_bf16 v[82:85], v[172:175], v[198:201], v[82:85]
	v_mfma_f32_16x16x32_bf16 v[70:73], v[150:153], v[220:223], v[70:73]
	v_mfma_f32_16x16x32_bf16 v[66:69], v[172:175], v[220:223], v[66:69]
	s_setprio 0
	s_barrier
	s_add_i32 s18, s90, s26
	v_lshl_add_u64 v[202:203], s[22:23], 0, v[160:161]
	s_mov_b32 m0, s18
	ds_read_b128 v[176:179], v189 offset:16384
	ds_read_b128 v[180:183], v189 offset:17408
	ds_read_b128 v[184:187], v189 offset:18432
	ds_read_b128 v[190:193], v189 offset:19456
	ds_read_b128 v[194:197], v189 offset:20480
	ds_read_b128 v[198:201], v189 offset:21504
	ds_read_b128 v[216:219], v189 offset:22528
	ds_read_b128 v[220:223], v189 offset:23552
	global_load_lds_dwordx4 v[202:203], off
	s_add_i32 m0, s18, 0x2000
	s_add_u32 s18, s22, 0xb0000
	v_lshl_add_u64 v[208:209], s[22:23], 0, v[164:165]
	s_addc_u32 s19, s23, 0
	s_add_i32 s45, s81, s26
	global_load_lds_dwordx4 v[208:209], off
	v_lshl_add_u64 v[210:211], s[18:19], 0, v[160:161]
	s_mov_b32 m0, s45
	v_lshl_add_u64 v[224:225], s[24:25], 0, v[162:163]
	global_load_lds_dwordx4 v[210:211], off
	v_lshl_add_u64 v[210:211], s[18:19], 0, v[164:165]
	s_add_i32 m0, s45, 0x2000
	s_nop 0
	global_load_lds_dwordx4 v[210:211], off
	v_lshl_add_u64 v[210:211], s[24:25], 0, v[158:159]
	s_mov_b32 m0, s27
	s_nop 0
	global_load_lds_dwordx4 v[210:211], off
	s_mov_b32 m0, s28
	s_nop 0
	global_load_lds_dwordx4 v[224:225], off
	s_waitcnt vmcnt(8)
	s_waitcnt lgkmcnt(0)
	s_barrier
; #define PG8_STAGE(bufoff, gbase, voff) do { _Pragma("unroll") for (int _i = 0; _i < 2; ++_i) \
;         __builtin_amdgcn_global_load_lds((const unsigned*)((const char*)(gbase) + (voff)[_i]), (PG8_LAS unsigned*)(lds + (bufoff) + ldsw + _i * 8192), 16, 0, 0); } while (0)
; #define PG8_LDA(dst, b, h) do { _Pragma("unroll") for (int m = 0; m < 4; ++m) _Pragma("unroll") for (int k = 0; k < 2; ++k) dst[m][k] = *(const PG8_LAS bf16x8*)(lds + PG8_SA(b, h) + aoff + m * 2048 + k * 1024); } while (0)
; #define PG8_LDB(dst, b, h) do { _Pragma("unroll") for (int n = 0; n < 2; ++n) _Pragma("unroll") for (int k = 0; k < 2; ++k) dst[n][k] = *(const PG8_LAS bf16x8*)(lds + PG8_SB(b, h) + boff + n * 2048 + k * 1024); } while (0)
; #define PG8_MMA(ai, bj, At, Bt) do { __builtin_amdgcn_s_setprio(1); _Pragma("unroll") for (int m = 0; m < 4; ++m) _Pragma("unroll") for (int n = 0; n < 2; ++n) _Pragma("unroll") for (int k = 0; k < 2; ++k) \
;         acc[ai][bj][m][n] = __builtin_amdgcn_mfma_f32_16x16x32_bf16(Bt[n][k], At[m][k], acc[ai][bj][m][n], 0, 0, 0); __builtin_amdgcn_s_setprio(0); } while (0)
; #define PG8_WAIT_V(n) asm volatile("s_waitcnt vmcnt(" #n ")" ::: "memory")
; #define PG8_WAIT_L(n) asm volatile("s_waitcnt lgkmcnt(" #n ")" ::: "memory")
; #define PG8_BAR __builtin_amdgcn_s_barrier()
; #define PG8_SCHED __builtin_amdgcn_sched_barrier(0)
; template <class Epi, class Sched, bool ALIGN_EPI = false, bool SP2 = false>
; __device__ __forceinline__ void gemm_phase(PG8_LAS unsigned char* lds, const Gemm g, const Sched& S, const Epi& E) {
;     ...
;             PG8_WAIT_V(8); PG8_WAIT_L(0); PG8_BAR; PG8_MMA(1, 0, At, B0); PG8_MMA(1, 1, At, B1); PG8_BAR; PG8_SCHED;
;             PG8_LDB(B0, 1, 0); PG8_LDB(B1, 1, 1); PG8_SCHED; PG8_LDA(At, 1, 0); PG8_STAGE(PG8_SA(0, 1), a2 + hstep, voffA);
;             PG8_WAIT_V(8); PG8_WAIT_L(0); PG8_BAR; PG8_MMA(0, 0, At, B0); PG8_MMA(0, 1, At, B1); PG8_BAR; PG8_SCHED;
	s_setprio 1
	s_waitcnt lgkmcnt(0)
	v_mfma_f32_16x16x32_bf16 v[62:65], v[130:133], v[176:179], 0
	v_mfma_f32_16x16x32_bf16 v[58:61], v[138:141], v[176:179], 0
	v_mfma_f32_16x16x32_bf16 v[46:49], v[130:133], v[184:187], 0
	v_mfma_f32_16x16x32_bf16 v[42:45], v[138:141], v[184:187], 0
	v_mfma_f32_16x16x32_bf16 v[30:33], v[130:133], v[194:197], 0
	v_mfma_f32_16x16x32_bf16 v[26:29], v[138:141], v[194:197], 0
	v_mfma_f32_16x16x32_bf16 v[14:17], v[130:133], v[216:219], 0
	v_mfma_f32_16x16x32_bf16 v[10:13], v[138:141], v[216:219], 0
	v_mfma_f32_16x16x32_bf16 v[62:65], v[134:137], v[180:183], v[62:65]
	v_mfma_f32_16x16x32_bf16 v[58:61], v[142:145], v[180:183], v[58:61]
	v_mfma_f32_16x16x32_bf16 v[46:49], v[134:137], v[190:193], v[46:49]
	v_mfma_f32_16x16x32_bf16 v[42:45], v[142:145], v[190:193], v[42:45]
	v_mfma_f32_16x16x32_bf16 v[30:33], v[134:137], v[198:201], v[30:33]
	v_mfma_f32_16x16x32_bf16 v[26:29], v[142:145], v[198:201], v[26:29]
	v_mfma_f32_16x16x32_bf16 v[14:17], v[134:137], v[220:223], v[14:17]
	v_mfma_f32_16x16x32_bf16 v[10:13], v[142:145], v[220:223], v[10:13]
	s_setprio 0
	s_setprio 1
	v_mfma_f32_16x16x32_bf16 v[54:57], v[146:149], v[176:179], 0
	v_mfma_f32_16x16x32_bf16 v[50:53], v[154:157], v[176:179], 0
	v_mfma_f32_16x16x32_bf16 v[38:41], v[146:149], v[184:187], 0
	v_mfma_f32_16x16x32_bf16 v[34:37], v[154:157], v[184:187], 0
	v_mfma_f32_16x16x32_bf16 v[22:25], v[146:149], v[194:197], 0
	v_mfma_f32_16x16x32_bf16 v[18:21], v[154:157], v[194:197], 0
	v_mfma_f32_16x16x32_bf16 v[6:9], v[146:149], v[216:219], 0
	v_mfma_f32_16x16x32_bf16 v[2:5], v[154:157], v[216:219], 0
	v_mfma_f32_16x16x32_bf16 v[54:57], v[150:153], v[180:183], v[54:57]
	v_mfma_f32_16x16x32_bf16 v[50:53], v[172:175], v[180:183], v[50:53]
	v_mfma_f32_16x16x32_bf16 v[38:41], v[150:153], v[190:193], v[38:41]
	v_mfma_f32_16x16x32_bf16 v[34:37], v[172:175], v[190:193], v[34:37]
	v_mfma_f32_16x16x32_bf16 v[22:25], v[150:153], v[198:201], v[22:25]
	v_mfma_f32_16x16x32_bf16 v[18:21], v[172:175], v[198:201], v[18:21]
	v_mfma_f32_16x16x32_bf16 v[6:9], v[150:153], v[220:223], v[6:9]
	v_mfma_f32_16x16x32_bf16 v[2:5], v[172:175], v[220:223], v[2:5]
	s_setprio 0
	s_barrier
	v_add_u32_e32 v142, s82, v188
	v_add_u32_e32 v172, s83, v188
	ds_read_b128 v[130:133], v142
	ds_read_b128 v[134:137], v142 offset:1024
	ds_read_b128 v[138:141], v142 offset:2048
	ds_read_b128 v[142:145], v142 offset:3072
	ds_read_b128 v[146:149], v172
	ds_read_b128 v[150:153], v172 offset:1024
	ds_read_b128 v[154:157], v172 offset:2048
	ds_read_b128 v[172:175], v172 offset:3072
	s_add_u32 s18, s24, 0xb0000
	s_addc_u32 s19, s25, 0
	s_mov_b32 m0, s29
	v_lshl_add_u64 v[226:227], s[18:19], 0, v[158:159]
	ds_read_b128 v[176:179], v189 offset:32768
	ds_read_b128 v[180:183], v189 offset:33792
	ds_read_b128 v[184:187], v189 offset:34816
	ds_read_b128 v[190:193], v189 offset:35840
	ds_read_b128 v[194:197], v189 offset:36864
	ds_read_b128 v[198:201], v189 offset:37888
	ds_read_b128 v[216:219], v189 offset:38912
	ds_read_b128 v[220:223], v189 offset:39936
	global_load_lds_dwordx4 v[226:227], off
	v_lshl_add_u64 v[226:227], s[18:19], 0, v[162:163]
	s_mov_b32 m0, s30
	s_nop 0
	global_load_lds_dwordx4 v[226:227], off
	s_waitcnt vmcnt(8)
	s_waitcnt lgkmcnt(0)
	s_barrier
	s_setprio 1
	s_waitcnt lgkmcnt(0)
	v_mfma_f32_16x16x32_bf16 v[126:129], v[130:133], v[176:179], v[126:129]
	v_mfma_f32_16x16x32_bf16 v[122:125], v[138:141], v[176:179], v[122:125]
	v_mfma_f32_16x16x32_bf16 v[110:113], v[130:133], v[184:187], v[110:113]
	v_mfma_f32_16x16x32_bf16 v[106:109], v[138:141], v[184:187], v[106:109]
	v_mfma_f32_16x16x32_bf16 v[94:97], v[130:133], v[194:197], v[94:97]
	v_mfma_f32_16x16x32_bf16 v[90:93], v[138:141], v[194:197], v[90:93]
	v_mfma_f32_16x16x32_bf16 v[78:81], v[130:133], v[216:219], v[78:81]
	v_mfma_f32_16x16x32_bf16 v[74:77], v[138:141], v[216:219], v[74:77]
	v_mfma_f32_16x16x32_bf16 v[126:129], v[134:137], v[180:183], v[126:129]
	v_mfma_f32_16x16x32_bf16 v[122:125], v[142:145], v[180:183], v[122:125]
	v_mfma_f32_16x16x32_bf16 v[110:113], v[134:137], v[190:193], v[110:113]
	v_mfma_f32_16x16x32_bf16 v[106:109], v[142:145], v[190:193], v[106:109]
	v_mfma_f32_16x16x32_bf16 v[94:97], v[134:137], v[198:201], v[94:97]
	v_mfma_f32_16x16x32_bf16 v[90:93], v[142:145], v[198:201], v[90:93]
	v_mfma_f32_16x16x32_bf16 v[78:81], v[134:137], v[220:223], v[78:81]
	v_mfma_f32_16x16x32_bf16 v[74:77], v[142:145], v[220:223], v[74:77]
	s_setprio 0
	s_setprio 1
	v_mfma_f32_16x16x32_bf16 v[118:121], v[146:149], v[176:179], v[118:121]
	v_mfma_f32_16x16x32_bf16 v[114:117], v[154:157], v[176:179], v[114:117]
	v_mfma_f32_16x16x32_bf16 v[102:105], v[146:149], v[184:187], v[102:105]
	v_mfma_f32_16x16x32_bf16 v[98:101], v[154:157], v[184:187], v[98:101]
	v_mfma_f32_16x16x32_bf16 v[86:89], v[146:149], v[194:197], v[86:89]
	v_mfma_f32_16x16x32_bf16 v[82:85], v[154:157], v[194:197], v[82:85]
	v_mfma_f32_16x16x32_bf16 v[70:73], v[146:149], v[216:219], v[70:73]
	v_mfma_f32_16x16x32_bf16 v[66:69], v[154:157], v[216:219], v[66:69]
	v_mfma_f32_16x16x32_bf16 v[118:121], v[150:153], v[180:183], v[118:121]
	v_mfma_f32_16x16x32_bf16 v[114:117], v[172:175], v[180:183], v[114:117]
	v_mfma_f32_16x16x32_bf16 v[102:105], v[150:153], v[190:193], v[102:105]
	v_mfma_f32_16x16x32_bf16 v[98:101], v[172:175], v[190:193], v[98:101]
	v_mfma_f32_16x16x32_bf16 v[86:89], v[150:153], v[198:201], v[86:89]
	v_mfma_f32_16x16x32_bf16 v[82:85], v[172:175], v[198:201], v[82:85]
	v_mfma_f32_16x16x32_bf16 v[70:73], v[150:153], v[220:223], v[70:73]
	v_mfma_f32_16x16x32_bf16 v[66:69], v[172:175], v[220:223], v[66:69]
	s_setprio 0
	s_barrier
; #define PG8_STAGE(bufoff, gbase, voff) do { _Pragma("unroll") for (int _i = 0; _i < 2; ++_i) \
;         __builtin_amdgcn_global_load_lds((const unsigned*)((const char*)(gbase) + (voff)[_i]), (PG8_LAS unsigned*)(lds + (bufoff) + ldsw + _i * 8192), 16, 0, 0); } while (0)
; #define PG8_LDA(dst, b, h) do { _Pragma("unroll") for (int m = 0; m < 4; ++m) _Pragma("unroll") for (int k = 0; k < 2; ++k) dst[m][k] = *(const PG8_LAS bf16x8*)(lds + PG8_SA(b, h) + aoff + m * 2048 + k * 1024); } while (0)
; #define PG8_MMA(ai, bj, At, Bt) do { __builtin_amdgcn_s_setprio(1); _Pragma("unroll") for (int m = 0; m < 4; ++m) _Pragma("unroll") for (int n = 0; n < 2; ++n) _Pragma("unroll") for (int k = 0; k < 2; ++k) \
;         acc[ai][bj][m][n] = __builtin_amdgcn_mfma_f32_16x16x32_bf16(Bt[n][k], At[m][k], acc[ai][bj][m][n], 0, 0, 0); __builtin_amdgcn_s_setprio(0); } while (0)
; #define PG8_WAIT_V(n) asm volatile("s_waitcnt vmcnt(" #n ")" ::: "memory")
; #define PG8_WAIT_L(n) asm volatile("s_waitcnt lgkmcnt(" #n ")" ::: "memory")
; #define PG8_BAR __builtin_amdgcn_s_barrier()
; #define PG8_SCHED __builtin_amdgcn_sched_barrier(0)
; template <class Epi, class Sched, bool ALIGN_EPI = false, bool SP2 = false>
; __device__ __forceinline__ void gemm_phase(PG8_LAS unsigned char* lds, const Gemm g, const Sched& S, const Epi& E) {
;     ...
;             PG8_LDA(At, 1, 1); PG8_STAGE(PG8_SB(1, 0), b3, voffB); PG8_STAGE(PG8_SB(1, 1), b3 + hstep, voffB); PG8_STAGE(PG8_SA(1, 0), a3, voffA);
;             PG8_WAIT_V(8); PG8_WAIT_L(0); PG8_BAR; PG8_MMA(1, 0, At, B0); PG8_MMA(1, 1, At, B1); PG8_BAR; PG8_SCHED;
	s_add_i32 s18, s82, s26
	v_lshl_add_u64 v[202:203], v[202:203], 0, s[46:47]
	s_mov_b32 m0, s18
	ds_read_b128 v[176:179], v189 offset:49152
	ds_read_b128 v[180:183], v189 offset:50176
	ds_read_b128 v[184:187], v189 offset:51200
	ds_read_b128 v[190:193], v189 offset:52224
	ds_read_b128 v[194:197], v189 offset:53248
	ds_read_b128 v[198:201], v189 offset:54272
	ds_read_b128 v[216:219], v189 offset:55296
	ds_read_b128 v[220:223], v189 offset:56320
	global_load_lds_dwordx4 v[202:203], off
	s_add_i32 m0, s18, 0x2000
	s_add_u32 s18, s22, 0xb0080
	v_lshl_add_u64 v[202:203], v[208:209], 0, s[46:47]
	s_addc_u32 s19, s23, 0
	s_add_i32 s22, s83, s26
	global_load_lds_dwordx4 v[202:203], off
	v_lshl_add_u64 v[202:203], s[18:19], 0, v[160:161]
	s_mov_b32 m0, s22
	s_nop 0
	global_load_lds_dwordx4 v[202:203], off
	v_lshl_add_u64 v[202:203], s[18:19], 0, v[164:165]
	s_add_i32 m0, s22, 0x2000
	s_nop 0
	global_load_lds_dwordx4 v[202:203], off
	v_lshl_add_u64 v[202:203], v[210:211], 0, s[46:47]
	s_mov_b32 m0, s31
	s_nop 0
	global_load_lds_dwordx4 v[202:203], off
	v_lshl_add_u64 v[202:203], v[224:225], 0, s[46:47]
	s_mov_b32 m0, s34
	s_nop 0
	global_load_lds_dwordx4 v[202:203], off
	s_waitcnt vmcnt(8)
	s_waitcnt lgkmcnt(0)
	s_barrier
	s_setprio 1
	s_waitcnt lgkmcnt(0)
	v_mfma_f32_16x16x32_bf16 v[62:65], v[130:133], v[176:179], v[62:65]
	v_mfma_f32_16x16x32_bf16 v[58:61], v[138:141], v[176:179], v[58:61]
	v_mfma_f32_16x16x32_bf16 v[46:49], v[130:133], v[184:187], v[46:49]
	v_mfma_f32_16x16x32_bf16 v[42:45], v[138:141], v[184:187], v[42:45]
	v_mfma_f32_16x16x32_bf16 v[30:33], v[130:133], v[194:197], v[30:33]
	v_mfma_f32_16x16x32_bf16 v[26:29], v[138:141], v[194:197], v[26:29]
	v_mfma_f32_16x16x32_bf16 v[14:17], v[130:133], v[216:219], v[14:17]
	v_mfma_f32_16x16x32_bf16 v[10:13], v[138:141], v[216:219], v[10:13]
	v_mfma_f32_16x16x32_bf16 v[62:65], v[134:137], v[180:183], v[62:65]
	v_mfma_f32_16x16x32_bf16 v[58:61], v[142:145], v[180:183], v[58:61]
	v_mfma_f32_16x16x32_bf16 v[46:49], v[134:137], v[190:193], v[46:49]
	v_mfma_f32_16x16x32_bf16 v[42:45], v[142:145], v[190:193], v[42:45]
	v_mfma_f32_16x16x32_bf16 v[30:33], v[134:137], v[198:201], v[30:33]
	v_mfma_f32_16x16x32_bf16 v[26:29], v[142:145], v[198:201], v[26:29]
	v_mfma_f32_16x16x32_bf16 v[14:17], v[134:137], v[220:223], v[14:17]
	v_mfma_f32_16x16x32_bf16 v[10:13], v[142:145], v[220:223], v[10:13]
	s_setprio 0
	s_setprio 1
	v_mfma_f32_16x16x32_bf16 v[54:57], v[146:149], v[176:179], v[54:57]
	v_mfma_f32_16x16x32_bf16 v[50:53], v[154:157], v[176:179], v[50:53]
	v_mfma_f32_16x16x32_bf16 v[38:41], v[146:149], v[184:187], v[38:41]
	v_mfma_f32_16x16x32_bf16 v[34:37], v[154:157], v[184:187], v[34:37]
	v_mfma_f32_16x16x32_bf16 v[22:25], v[146:149], v[194:197], v[22:25]
	v_mfma_f32_16x16x32_bf16 v[18:21], v[154:157], v[194:197], v[18:21]
	v_mfma_f32_16x16x32_bf16 v[6:9], v[146:149], v[216:219], v[6:9]
	v_mfma_f32_16x16x32_bf16 v[2:5], v[154:157], v[216:219], v[2:5]
	v_mfma_f32_16x16x32_bf16 v[54:57], v[150:153], v[180:183], v[54:57]
	v_mfma_f32_16x16x32_bf16 v[50:53], v[172:175], v[180:183], v[50:53]
	v_mfma_f32_16x16x32_bf16 v[38:41], v[150:153], v[190:193], v[38:41]
	v_mfma_f32_16x16x32_bf16 v[34:37], v[172:175], v[190:193], v[34:37]
	v_mfma_f32_16x16x32_bf16 v[22:25], v[150:153], v[198:201], v[22:25]
	v_mfma_f32_16x16x32_bf16 v[18:21], v[172:175], v[198:201], v[18:21]
	v_mfma_f32_16x16x32_bf16 v[6:9], v[150:153], v[220:223], v[6:9]
	v_mfma_f32_16x16x32_bf16 v[2:5], v[172:175], v[220:223], v[2:5]
	s_setprio 0
	s_barrier
	s_add_i32 s44, s44, 2
	s_add_u32 s39, s39, 0x100
	s_addc_u32 s42, s42, 0
	s_mov_b64 s[18:19], s[20:21]
